# v90 (SGPR-base DMA in all K-loops, no setprio, accumulator-stationary MFMA order) + int8 pair k-order alternation
# baseline (speedup 1.0000x reference)
; #define PG8_STAGE(bufoff, gbase, voff) do { _Pragma("unroll") for (int _i = 0; _i < 2; ++_i) \
;         __builtin_amdgcn_global_load_lds((const unsigned*)((const char*)(gbase) + (voff)[_i]), (PG8_LAS unsigned*)(lds + (bufoff) + ldsw + _i * 8192), 16, 0, 0); } while (0)
; #define PG8_LDA(dst, b, h) do { _Pragma("unroll") for (int m = 0; m < 4; ++m) _Pragma("unroll") for (int k = 0; k < 2; ++k) dst[m][k] = *(const PG8_LAS bf16x8*)(lds + PG8_SA(b, h) + aoff + m * 2048 + k * 1024); } while (0)
; #define PG8_LDB(dst, b, h) do { _Pragma("unroll") for (int n = 0; n < 2; ++n) _Pragma("unroll") for (int k = 0; k < 2; ++k) dst[n][k] = *(const PG8_LAS bf16x8*)(lds + PG8_SB(b, h) + boff + n * 2048 + k * 1024); } while (0)
; #define PG8_MMA(ai, bj, At, Bt) do { __builtin_amdgcn_s_setprio(1); _Pragma("unroll") for (int m = 0; m < 4; ++m) _Pragma("unroll") for (int n = 0; n < 2; ++n) _Pragma("unroll") for (int k = 0; k < 2; ++k) \
;         acc[ai][bj][m][n] = mma16<Epi::I8>(Bt[n][k], At[m][k], acc[ai][bj][m][n]); __builtin_amdgcn_s_setprio(0); } while (0)
; #define PG8_WAIT_V(n) asm volatile("s_waitcnt vmcnt(" #n ")" ::: "memory")
; #define PG8_WAIT_L(n) asm volatile("s_waitcnt lgkmcnt(" #n ")" ::: "memory")
; template <class Epi, class Sched, bool ALIGN_EPI = false, bool SP2 = false>
; __device__ __forceinline__ void gemm_phase(PG8_LAS unsigned char* lds, const Gemm g, const Sched& S, const Epi& E) {
;     ...
;         for (int t = 0; t < nt; t += 2) {
;             const bool last = (t == nt - 2);
;             const char* a1 = cA + (size_t)(t + 1) * kstep;
;             const char* a2 = last ? nA : cA + (size_t)(t + 2) * kstep; const char* b2 = last ? nB : cB + (size_t)(t + 2) * kstep;
;             const char* a3 = a2 + kstep; const char* b3 = b2 + kstep;
;             if (last && has_next) S.a_ready(nxt);
;             if constexpr (SP2) {
;             PG8_LDB(B0, 0, 0); PG8_LDB(B1, 0, 1); PG8_SCHED; PG8_LDA(At, 0, 0); PG8_STAGE(PG8_SA(1, 1), a1 + hstep, voffA);
;             PG8_WAIT_V(8); PG8_WAIT_L(0); PG8_BAR; PG8_MMA(0, 0, At, B0); PG8_MMA(0, 1, At, B1); PG8_BAR; PG8_SCHED;
;             PG8_LDA(At, 0, 1); PG8_STAGE(PG8_SB(0, 0), b2, voffB); PG8_STAGE(PG8_SB(0, 1), b2 + hstep, voffB); PG8_STAGE(PG8_SA(0, 0), a2, voffA);
;             PG8_WAIT_V(8); PG8_WAIT_L(0); PG8_BAR; PG8_MMA(1, 0, At, B0); PG8_MMA(1, 1, At, B1); PG8_BAR; PG8_SCHED;
.Lpeel80:
	s_add_u32 s8, s0, 0x100
	s_addc_u32 s9, s1, 0
	s_add_i32 vcc_hi, 0, 0x10000
	s_cmp_eq_u32 vcc_lo, 12
	s_cselect_b32 s13, s66, s9
	s_cselect_b32 s12, s67, s8
	s_cselect_b32 s7, s82, s97
	s_cselect_b32 s6, s83, s96
	s_add_i32 s4, 0, 0x14000
	v_add_u32_e32 v38, vcc_hi, v242
	v_add_u32_e32 v158, s4, v242
	ds_read_b128 v[18:21], v38
	ds_read_b128 v[22:25], v38 offset:1024
	ds_read_b128 v[34:37], v38 offset:2048
	ds_read_b128 v[38:41], v38 offset:3072
	ds_read_b128 v[130:133], v158
	ds_read_b128 v[134:137], v158 offset:1024
	ds_read_b128 v[154:157], v158 offset:2048
	ds_read_b128 v[158:161], v158 offset:3072
	s_add_i32 m0, s11, 0xc000
	ds_read_b128 v[162:165], v243
	ds_read_b128 v[166:169], v243 offset:1024
	ds_read_b128 v[170:173], v243 offset:2048
	ds_read_b128 v[174:177], v243 offset:3072
	ds_read_b128 v[178:181], v243 offset:4096
	ds_read_b128 v[182:185], v243 offset:5120
	ds_read_b128 v[186:189], v243 offset:6144
	ds_read_b128 v[190:193], v243 offset:7168
	global_load_lds_dwordx4 v216, s[0:1]
	s_add_i32 m0, s11, 0xe000
	s_nop 0
	global_load_lds_dwordx4 v218, s[0:1]
	s_waitcnt vmcnt(8)
	s_waitcnt lgkmcnt(0)
	s_barrier
	s_waitcnt lgkmcnt(0)
	v_mfma_i32_16x16x64_i8 v[150:153], v[18:21], v[162:165], 0
	v_mfma_i32_16x16x64_i8 v[150:153], v[22:25], v[166:169], v[150:153]
	v_mfma_i32_16x16x64_i8 v[146:149], v[38:41], v[166:169], 0
	v_mfma_i32_16x16x64_i8 v[146:149], v[34:37], v[162:165], v[146:149]
	v_mfma_i32_16x16x64_i8 v[110:113], v[34:37], v[170:173], 0
	v_mfma_i32_16x16x64_i8 v[110:113], v[38:41], v[174:177], v[110:113]
	v_mfma_i32_16x16x64_i8 v[118:121], v[22:25], v[174:177], 0
	v_mfma_i32_16x16x64_i8 v[118:121], v[18:21], v[170:173], v[118:121]
	v_mfma_i32_16x16x64_i8 v[54:57], v[18:21], v[178:181], 0
	v_mfma_i32_16x16x64_i8 v[54:57], v[22:25], v[182:185], v[54:57]
	v_mfma_i32_16x16x64_i8 v[30:33], v[38:41], v[182:185], 0
	v_mfma_i32_16x16x64_i8 v[30:33], v[34:37], v[178:181], v[30:33]
	v_mfma_i32_16x16x64_i8 v[58:61], v[34:37], v[186:189], 0
	v_mfma_i32_16x16x64_i8 v[58:61], v[38:41], v[190:193], v[58:61]
	v_mfma_i32_16x16x64_i8 v[94:97], v[22:25], v[190:193], 0
	v_mfma_i32_16x16x64_i8 v[94:97], v[18:21], v[186:189], v[94:97]
	v_mfma_i32_16x16x64_i8 v[62:65], v[154:157], v[186:189], 0
	v_mfma_i32_16x16x64_i8 v[62:65], v[158:161], v[190:193], v[62:65]
	v_mfma_i32_16x16x64_i8 v[138:141], v[158:161], v[166:169], 0
	v_mfma_i32_16x16x64_i8 v[138:141], v[154:157], v[162:165], v[138:141]
	v_mfma_i32_16x16x64_i8 v[142:145], v[130:133], v[162:165], 0
	v_mfma_i32_16x16x64_i8 v[142:145], v[134:137], v[166:169], v[142:145]
	v_mfma_i32_16x16x64_i8 v[102:105], v[134:137], v[174:177], 0
	v_mfma_i32_16x16x64_i8 v[102:105], v[130:133], v[170:173], v[102:105]
	v_mfma_i32_16x16x64_i8 v[98:101], v[154:157], v[170:173], 0
	v_mfma_i32_16x16x64_i8 v[98:101], v[158:161], v[174:177], v[98:101]
	v_mfma_i32_16x16x64_i8 v[26:29], v[158:161], v[182:185], 0
	v_mfma_i32_16x16x64_i8 v[26:29], v[154:157], v[178:181], v[26:29]
	v_mfma_i32_16x16x64_i8 v[42:45], v[130:133], v[178:181], 0
	v_mfma_i32_16x16x64_i8 v[42:45], v[134:137], v[182:185], v[42:45]
	v_mfma_i32_16x16x64_i8 v[78:81], v[134:137], v[190:193], 0
	v_mfma_i32_16x16x64_i8 v[78:81], v[130:133], v[186:189], v[78:81]
	s_barrier
	s_add_i32 s0, vcc_hi, s69
	s_mov_b32 m0, s0
	ds_read_b128 v[162:165], v243 offset:16384
	ds_read_b128 v[166:169], v243 offset:17408
	ds_read_b128 v[170:173], v243 offset:18432
	ds_read_b128 v[174:177], v243 offset:19456
	ds_read_b128 v[178:181], v243 offset:20480
	ds_read_b128 v[182:185], v243 offset:21504
	ds_read_b128 v[186:189], v243 offset:22528
	ds_read_b128 v[190:193], v243 offset:23552
	global_load_lds_dwordx4 v0, s[6:7]
	s_add_i32 m0, s0, 0x2000
	s_add_u32 s0, s6, 0x40000
	s_addc_u32 s1, s7, 0
	s_add_i32 s4, s4, s69
	global_load_lds_dwordx4 v214, s[6:7]
	s_mov_b32 m0, s4
	s_nop 0
	global_load_lds_dwordx4 v0, s[0:1]
	s_add_i32 m0, s4, 0x2000
	s_nop 0
	global_load_lds_dwordx4 v214, s[0:1]
	s_mov_b32 m0, s11
	s_nop 0
	global_load_lds_dwordx4 v210, s[12:13]
	s_mov_b32 m0, s71
	s_nop 0
	global_load_lds_dwordx4 v212, s[12:13]
	s_waitcnt vmcnt(8)
	s_waitcnt lgkmcnt(0)
	s_barrier
	s_waitcnt lgkmcnt(0)
	v_mfma_i32_16x16x64_i8 v[106:109], v[18:21], v[162:165], 0
	v_mfma_i32_16x16x64_i8 v[106:109], v[22:25], v[166:169], v[106:109]
	v_mfma_i32_16x16x64_i8 v[46:49], v[34:37], v[162:165], 0
	v_mfma_i32_16x16x64_i8 v[46:49], v[38:41], v[166:169], v[46:49]
	v_mfma_i32_16x16x64_i8 v[6:9], v[34:37], v[170:173], 0
	v_mfma_i32_16x16x64_i8 v[6:9], v[38:41], v[174:177], v[6:9]
	v_mfma_i32_16x16x64_i8 v[14:17], v[18:21], v[170:173], 0
	v_mfma_i32_16x16x64_i8 v[14:17], v[22:25], v[174:177], v[14:17]
	v_mfma_i32_16x16x64_i8 v[90:93], v[18:21], v[178:181], 0
	v_mfma_i32_16x16x64_i8 v[90:93], v[22:25], v[182:185], v[90:93]
	v_mfma_i32_16x16x64_i8 v[86:89], v[34:37], v[178:181], 0
	v_mfma_i32_16x16x64_i8 v[86:89], v[38:41], v[182:185], v[86:89]
	v_mfma_i32_16x16x64_i8 v[18:21], v[18:21], v[186:189], 0
	v_mfma_i32_16x16x64_i8 v[18:21], v[22:25], v[190:193], v[18:21]
	v_mfma_i32_16x16x64_i8 v[22:25], v[34:37], v[186:189], 0
	v_mfma_i32_16x16x64_i8 v[22:25], v[38:41], v[190:193], v[22:25]
	v_mfma_i32_16x16x64_i8 v[38:41], v[154:157], v[162:165], 0
	v_mfma_i32_16x16x64_i8 v[38:41], v[158:161], v[166:169], v[38:41]
	v_mfma_i32_16x16x64_i8 v[2:5], v[154:157], v[170:173], 0
	v_mfma_i32_16x16x64_i8 v[2:5], v[158:161], v[174:177], v[2:5]
	v_mfma_i32_16x16x64_i8 v[10:13], v[130:133], v[170:173], 0
	v_mfma_i32_16x16x64_i8 v[10:13], v[134:137], v[174:177], v[10:13]
	v_mfma_i32_16x16x64_i8 v[50:53], v[130:133], v[178:181], 0
	v_mfma_i32_16x16x64_i8 v[82:85], v[134:137], v[182:185], v[50:53]
	v_mfma_i32_16x16x64_i8 v[34:37], v[130:133], v[162:165], 0
	v_mfma_i32_16x16x64_i8 v[34:37], v[134:137], v[166:169], v[34:37]
	v_mfma_i32_16x16x64_i8 v[50:53], v[154:157], v[178:181], 0
	v_mfma_i32_16x16x64_i8 v[74:77], v[158:161], v[182:185], v[50:53]
	v_mfma_i32_16x16x64_i8 v[50:53], v[130:133], v[186:189], 0
	v_mfma_i32_16x16x64_i8 v[122:125], v[134:137], v[190:193], v[50:53]
	v_mfma_i32_16x16x64_i8 v[50:53], v[154:157], v[186:189], 0
	v_mfma_i32_16x16x64_i8 v[70:73], v[158:161], v[190:193], v[50:53]
	s_barrier
; #define PG8_STAGE(bufoff, gbase, voff) do { _Pragma("unroll") for (int _i = 0; _i < 2; ++_i) \
;         __builtin_amdgcn_global_load_lds((const unsigned*)((const char*)(gbase) + (voff)[_i]), (PG8_LAS unsigned*)(lds + (bufoff) + ldsw + _i * 8192), 16, 0, 0); } while (0)
; #define PG8_LDA(dst, b, h) do { _Pragma("unroll") for (int m = 0; m < 4; ++m) _Pragma("unroll") for (int k = 0; k < 2; ++k) dst[m][k] = *(const PG8_LAS bf16x8*)(lds + PG8_SA(b, h) + aoff + m * 2048 + k * 1024); } while (0)
; #define PG8_LDB(dst, b, h) do { _Pragma("unroll") for (int n = 0; n < 2; ++n) _Pragma("unroll") for (int k = 0; k < 2; ++k) dst[n][k] = *(const PG8_LAS bf16x8*)(lds + PG8_SB(b, h) + boff + n * 2048 + k * 1024); } while (0)
; #define PG8_MMA(ai, bj, At, Bt) do { __builtin_amdgcn_s_setprio(1); _Pragma("unroll") for (int m = 0; m < 4; ++m) _Pragma("unroll") for (int n = 0; n < 2; ++n) _Pragma("unroll") for (int k = 0; k < 2; ++k) \
;         acc[ai][bj][m][n] = mma16<Epi::I8>(Bt[n][k], At[m][k], acc[ai][bj][m][n]); __builtin_amdgcn_s_setprio(0); } while (0)
; #define PG8_WAIT_V(n) asm volatile("s_waitcnt vmcnt(" #n ")" ::: "memory")
; #define PG8_WAIT_L(n) asm volatile("s_waitcnt lgkmcnt(" #n ")" ::: "memory")
; #define PG8_BAR __builtin_amdgcn_s_barrier()
; #define PG8_SCHED __builtin_amdgcn_sched_barrier(0)
; template <class Epi, class Sched, bool ALIGN_EPI = false, bool SP2 = false>
; __device__ __forceinline__ void gemm_phase(PG8_LAS unsigned char* lds, const Gemm g, const Sched& S, const Epi& E) {
;     ...
;             PG8_LDB(B0, 1, 0); PG8_LDB(B1, 1, 1); PG8_SCHED; PG8_LDA(At, 1, 0); PG8_STAGE(PG8_SA(0, 1), a2 + hstep, voffA);
;             PG8_WAIT_V(8); PG8_WAIT_L(0); PG8_BAR; PG8_MMA(0, 0, At, B0); PG8_MMA(0, 1, At, B1); PG8_BAR; PG8_SCHED;
;             PG8_LDA(At, 1, 1); PG8_STAGE(PG8_SB(1, 0), b3, voffB); PG8_STAGE(PG8_SB(1, 1), b3 + hstep, voffB); PG8_STAGE(PG8_SA(1, 0), a3, voffA);
;             PG8_WAIT_V(8); PG8_WAIT_L(0); PG8_BAR; PG8_MMA(1, 0, At, B0); PG8_MMA(1, 1, At, B1); PG8_BAR; PG8_SCHED;
	s_add_i32 s4, 0, 0x18000
	v_add_u32_e32 v126, s4, v242
	s_add_i32 s5, 0, 0x1c000
	ds_read_b128 v[50:53], v126
	ds_read_b128 v[66:69], v126 offset:1024
	ds_read_b128 v[114:117], v126 offset:2048
	ds_read_b128 v[130:133], v126 offset:3072
	v_add_u32_e32 v126, s5, v242
	ds_read_b128 v[134:137], v126
	ds_read_b128 v[154:157], v126 offset:1024
	ds_read_b128 v[158:161], v126 offset:2048
	ds_read_b128 v[162:165], v126 offset:3072
	s_add_u32 s0, s12, 0x40000
	s_addc_u32 s1, s13, 0
	s_mov_b32 m0, s80
	ds_read_b128 v[126:129], v243 offset:32768
	ds_read_b128 v[166:169], v243 offset:33792
	ds_read_b128 v[170:173], v243 offset:34816
	ds_read_b128 v[174:177], v243 offset:35840
	ds_read_b128 v[178:181], v243 offset:36864
	ds_read_b128 v[182:185], v243 offset:37888
	ds_read_b128 v[186:189], v243 offset:38912
	ds_read_b128 v[190:193], v243 offset:39936
	global_load_lds_dwordx4 v210, s[0:1]
	s_mov_b32 m0, s81
	s_nop 0
	global_load_lds_dwordx4 v212, s[0:1]
	s_waitcnt vmcnt(8)
	s_waitcnt lgkmcnt(0)
	s_barrier
	s_waitcnt lgkmcnt(0)
	v_mfma_i32_16x16x64_i8 v[150:153], v[50:53], v[126:129], v[150:153]
	v_mfma_i32_16x16x64_i8 v[150:153], v[66:69], v[166:169], v[150:153]
	v_mfma_i32_16x16x64_i8 v[146:149], v[114:117], v[126:129], v[146:149]
	v_mfma_i32_16x16x64_i8 v[146:149], v[130:133], v[166:169], v[146:149]
	v_mfma_i32_16x16x64_i8 v[110:113], v[114:117], v[170:173], v[110:113]
	v_mfma_i32_16x16x64_i8 v[110:113], v[130:133], v[174:177], v[110:113]
	v_mfma_i32_16x16x64_i8 v[118:121], v[50:53], v[170:173], v[118:121]
	v_mfma_i32_16x16x64_i8 v[118:121], v[66:69], v[174:177], v[118:121]
	v_mfma_i32_16x16x64_i8 v[54:57], v[50:53], v[178:181], v[54:57]
	v_mfma_i32_16x16x64_i8 v[54:57], v[66:69], v[182:185], v[54:57]
	v_mfma_i32_16x16x64_i8 v[30:33], v[114:117], v[178:181], v[30:33]
	v_mfma_i32_16x16x64_i8 v[30:33], v[130:133], v[182:185], v[30:33]
	v_mfma_i32_16x16x64_i8 v[58:61], v[114:117], v[186:189], v[58:61]
	v_mfma_i32_16x16x64_i8 v[58:61], v[130:133], v[190:193], v[58:61]
	v_mfma_i32_16x16x64_i8 v[94:97], v[50:53], v[186:189], v[94:97]
	v_mfma_i32_16x16x64_i8 v[94:97], v[66:69], v[190:193], v[94:97]
	v_mfma_i32_16x16x64_i8 v[142:145], v[134:137], v[126:129], v[142:145]
	v_mfma_i32_16x16x64_i8 v[142:145], v[154:157], v[166:169], v[142:145]
	v_mfma_i32_16x16x64_i8 v[126:129], v[158:161], v[126:129], v[138:141]
	v_mfma_i32_16x16x64_i8 v[138:141], v[162:165], v[166:169], v[126:129]
	v_mfma_i32_16x16x64_i8 v[98:101], v[158:161], v[170:173], v[98:101]
	v_mfma_i32_16x16x64_i8 v[98:101], v[162:165], v[174:177], v[98:101]
	v_mfma_i32_16x16x64_i8 v[102:105], v[134:137], v[170:173], v[102:105]
	v_mfma_i32_16x16x64_i8 v[102:105], v[154:157], v[174:177], v[102:105]
	v_mfma_i32_16x16x64_i8 v[42:45], v[134:137], v[178:181], v[42:45]
	v_mfma_i32_16x16x64_i8 v[42:45], v[154:157], v[182:185], v[42:45]
	v_mfma_i32_16x16x64_i8 v[26:29], v[158:161], v[178:181], v[26:29]
	v_mfma_i32_16x16x64_i8 v[26:29], v[162:165], v[182:185], v[26:29]
	v_mfma_i32_16x16x64_i8 v[62:65], v[158:161], v[186:189], v[62:65]
	v_mfma_i32_16x16x64_i8 v[62:65], v[162:165], v[190:193], v[62:65]
	v_mfma_i32_16x16x64_i8 v[78:81], v[134:137], v[186:189], v[78:81]
	v_mfma_i32_16x16x64_i8 v[78:81], v[154:157], v[190:193], v[78:81]
	s_barrier
	s_add_u32 s98, s6, 0x80
	s_addc_u32 s99, s7, 0
	s_add_u32 s100, s12, 0x80
	s_addc_u32 s101, s13, 0
	s_add_i32 s0, s4, s69
	s_mov_b32 m0, s0
	ds_read_b128 v[166:169], v243 offset:49152
	ds_read_b128 v[170:173], v243 offset:50176
	ds_read_b128 v[174:177], v243 offset:51200
	ds_read_b128 v[178:181], v243 offset:52224
	ds_read_b128 v[182:185], v243 offset:53248
	ds_read_b128 v[186:189], v243 offset:54272
	ds_read_b128 v[190:193], v243 offset:55296
	ds_read_b128 v[194:197], v243 offset:56320
	global_load_lds_dwordx4 v0, s[98:99]
	s_add_i32 m0, s0, 0x2000
	s_add_u32 s0, s6, 0x40080
	s_addc_u32 s1, s7, 0
	s_add_i32 s4, s5, s69
	global_load_lds_dwordx4 v214, s[98:99]
	s_mov_b32 m0, s4
	s_nop 0
	global_load_lds_dwordx4 v0, s[0:1]
	s_add_i32 m0, s4, 0x2000
	s_nop 0
	global_load_lds_dwordx4 v214, s[0:1]
	s_mov_b32 m0, s84
	s_nop 0
	global_load_lds_dwordx4 v210, s[100:101]
	s_mov_b32 m0, s85
	s_nop 0
	global_load_lds_dwordx4 v212, s[100:101]
	s_waitcnt vmcnt(8)
	s_waitcnt lgkmcnt(0)
	s_barrier
	s_waitcnt lgkmcnt(0)
	v_mfma_i32_16x16x64_i8 v[18:21], v[50:53], v[190:193], v[18:21]
	v_mfma_i32_16x16x64_i8 v[126:129], v[66:69], v[194:197], v[18:21]
	v_mfma_i32_16x16x64_i8 v[106:109], v[50:53], v[166:169], v[106:109]
	v_mfma_i32_16x16x64_i8 v[106:109], v[66:69], v[170:173], v[106:109]
	v_mfma_i32_16x16x64_i8 v[46:49], v[114:117], v[166:169], v[46:49]
	v_mfma_i32_16x16x64_i8 v[46:49], v[130:133], v[170:173], v[46:49]
	v_mfma_i32_16x16x64_i8 v[6:9], v[114:117], v[174:177], v[6:9]
	v_mfma_i32_16x16x64_i8 v[6:9], v[130:133], v[178:181], v[6:9]
	v_mfma_i32_16x16x64_i8 v[14:17], v[50:53], v[174:177], v[14:17]
	v_mfma_i32_16x16x64_i8 v[14:17], v[66:69], v[178:181], v[14:17]
	v_mfma_i32_16x16x64_i8 v[90:93], v[50:53], v[182:185], v[90:93]
	v_mfma_i32_16x16x64_i8 v[90:93], v[66:69], v[186:189], v[90:93]
	v_mfma_i32_16x16x64_i8 v[86:89], v[114:117], v[182:185], v[86:89]
	v_mfma_i32_16x16x64_i8 v[86:89], v[130:133], v[186:189], v[86:89]
	v_mfma_i32_16x16x64_i8 v[18:21], v[114:117], v[190:193], v[22:25]
	v_mfma_i32_16x16x64_i8 v[66:69], v[130:133], v[194:197], v[18:21]
	v_mfma_i32_16x16x64_i8 v[18:21], v[134:137], v[166:169], v[34:37]
	v_mfma_i32_16x16x64_i8 v[114:117], v[154:157], v[170:173], v[18:21]
	v_mfma_i32_16x16x64_i8 v[10:13], v[134:137], v[174:177], v[10:13]
	v_mfma_i32_16x16x64_i8 v[10:13], v[154:157], v[178:181], v[10:13]
	v_mfma_i32_16x16x64_i8 v[2:5], v[158:161], v[174:177], v[2:5]
	v_mfma_i32_16x16x64_i8 v[2:5], v[162:165], v[178:181], v[2:5]
	v_mfma_i32_16x16x64_i8 v[18:21], v[158:161], v[166:169], v[38:41]
	v_mfma_i32_16x16x64_i8 v[50:53], v[162:165], v[170:173], v[18:21]
	v_mfma_i32_16x16x64_i8 v[18:21], v[134:137], v[182:185], v[82:85]
	v_mfma_i32_16x16x64_i8 v[82:85], v[154:157], v[186:189], v[18:21]
	v_mfma_i32_16x16x64_i8 v[18:21], v[158:161], v[182:185], v[74:77]
	v_mfma_i32_16x16x64_i8 v[74:77], v[162:165], v[186:189], v[18:21]
	v_mfma_i32_16x16x64_i8 v[18:21], v[134:137], v[190:193], v[122:125]
	v_mfma_i32_16x16x64_i8 v[122:125], v[154:157], v[194:197], v[18:21]
	v_mfma_i32_16x16x64_i8 v[18:21], v[158:161], v[190:193], v[70:73]
	v_mfma_i32_16x16x64_i8 v[70:73], v[162:165], v[194:197], v[18:21]
	s_barrier
	s_add_i32 vcc_lo, vcc_lo, 2
	s_add_u32 s96, s96, 0x100
	s_addc_u32 s97, s97, 0
	s_cmp_gt_u32 vcc_lo, 13
	s_mov_b64 s[0:1], s[8:9]
	s_cbranch_scc0 .LBB0_80
	s_branch .Lpeelx80
; #define PG8_STAGE(bufoff, gbase, voff) do { _Pragma("unroll") for (int _i = 0; _i < 2; ++_i) \
;         __builtin_amdgcn_global_load_lds((const unsigned*)((const char*)(gbase) + (voff)[_i]), (PG8_LAS unsigned*)(lds + (bufoff) + ldsw + _i * 8192), 16, 0, 0); } while (0)
; #define PG8_LDA(dst, b, h) do { _Pragma("unroll") for (int m = 0; m < 4; ++m) _Pragma("unroll") for (int k = 0; k < 2; ++k) dst[m][k] = *(const PG8_LAS bf16x8*)(lds + PG8_SA(b, h) + aoff + m * 2048 + k * 1024); } while (0)
; #define PG8_LDB(dst, b, h) do { _Pragma("unroll") for (int n = 0; n < 2; ++n) _Pragma("unroll") for (int k = 0; k < 2; ++k) dst[n][k] = *(const PG8_LAS bf16x8*)(lds + PG8_SB(b, h) + boff + n * 2048 + k * 1024); } while (0)
; #define PG8_MMA(ai, bj, At, Bt) do { __builtin_amdgcn_s_setprio(1); _Pragma("unroll") for (int m = 0; m < 4; ++m) _Pragma("unroll") for (int n = 0; n < 2; ++n) _Pragma("unroll") for (int k = 0; k < 2; ++k) \
;         acc[ai][bj][m][n] = mma16<Epi::I8>(Bt[n][k], At[m][k], acc[ai][bj][m][n]); __builtin_amdgcn_s_setprio(0); } while (0)
; #define PG8_WAIT_V(n) asm volatile("s_waitcnt vmcnt(" #n ")" ::: "memory")
; #define PG8_WAIT_L(n) asm volatile("s_waitcnt lgkmcnt(" #n ")" ::: "memory")
; template <class Epi, class Sched, bool ALIGN_EPI = false, bool SP2 = false>
; __device__ __forceinline__ void gemm_phase(PG8_LAS unsigned char* lds, const Gemm g, const Sched& S, const Epi& E) {
;     ...
;         for (int t = 0; t < nt; t += 2) {
;             const bool last = (t == nt - 2);
;             const char* a1 = cA + (size_t)(t + 1) * kstep;
;             const char* a2 = last ? nA : cA + (size_t)(t + 2) * kstep; const char* b2 = last ? nB : cB + (size_t)(t + 2) * kstep;
;             const char* a3 = a2 + kstep; const char* b3 = b2 + kstep;
;             if (last && has_next) S.a_ready(nxt);
;             if constexpr (SP2) {
;             PG8_LDB(B0, 0, 0); PG8_LDB(B1, 0, 1); PG8_SCHED; PG8_LDA(At, 0, 0); PG8_STAGE(PG8_SA(1, 1), a1 + hstep, voffA);
;             PG8_WAIT_V(8); PG8_WAIT_L(0); PG8_BAR; PG8_MMA(0, 0, At, B0); PG8_MMA(0, 1, At, B1); PG8_BAR; PG8_SCHED;
;             PG8_LDA(At, 0, 1); PG8_STAGE(PG8_SB(0, 0), b2, voffB); PG8_STAGE(PG8_SB(0, 1), b2 + hstep, voffB); PG8_STAGE(PG8_SA(0, 0), a2, voffA);
;             PG8_WAIT_V(8); PG8_WAIT_L(0); PG8_BAR; PG8_MMA(1, 0, At, B0); PG8_MMA(1, 1, At, B1); PG8_BAR; PG8_SCHED;
.LBB0_80:
	s_add_u32 s8, s0, 0x100
	s_addc_u32 s9, s1, 0
	s_add_i32 vcc_hi, 0, 0x10000
	s_cmp_eq_u32 vcc_lo, 12
	s_cselect_b32 s13, s66, s9
	s_cselect_b32 s12, s67, s8
	s_cselect_b32 s7, s82, s97
	s_cselect_b32 s6, s83, s96
	s_add_i32 s4, 0, 0x14000
	v_add_u32_e32 v38, vcc_hi, v242
	v_add_u32_e32 v158, s4, v242
	ds_read_b128 v[18:21], v38
	ds_read_b128 v[22:25], v38 offset:1024
	ds_read_b128 v[34:37], v38 offset:2048
	ds_read_b128 v[38:41], v38 offset:3072
	ds_read_b128 v[130:133], v158
	ds_read_b128 v[134:137], v158 offset:1024
	ds_read_b128 v[154:157], v158 offset:2048
	ds_read_b128 v[158:161], v158 offset:3072
	s_add_i32 m0, s11, 0xc000
	ds_read_b128 v[162:165], v243
	ds_read_b128 v[166:169], v243 offset:1024
	ds_read_b128 v[170:173], v243 offset:2048
	ds_read_b128 v[174:177], v243 offset:3072
	ds_read_b128 v[178:181], v243 offset:4096
	ds_read_b128 v[182:185], v243 offset:5120
	ds_read_b128 v[186:189], v243 offset:6144
	ds_read_b128 v[190:193], v243 offset:7168
	global_load_lds_dwordx4 v216, s[0:1]
	s_add_i32 m0, s11, 0xe000
	s_nop 0
	global_load_lds_dwordx4 v218, s[0:1]
	s_waitcnt vmcnt(8)
	s_waitcnt lgkmcnt(0)
	s_barrier
	s_waitcnt lgkmcnt(0)
	v_mfma_i32_16x16x64_i8 v[150:153], v[18:21], v[162:165], v[150:153]
	v_mfma_i32_16x16x64_i8 v[150:153], v[22:25], v[166:169], v[150:153]
	v_mfma_i32_16x16x64_i8 v[146:149], v[38:41], v[166:169], v[146:149]
	v_mfma_i32_16x16x64_i8 v[146:149], v[34:37], v[162:165], v[146:149]
	v_mfma_i32_16x16x64_i8 v[110:113], v[34:37], v[170:173], v[110:113]
	v_mfma_i32_16x16x64_i8 v[110:113], v[38:41], v[174:177], v[110:113]
	v_mfma_i32_16x16x64_i8 v[118:121], v[22:25], v[174:177], v[118:121]
	v_mfma_i32_16x16x64_i8 v[118:121], v[18:21], v[170:173], v[118:121]
	v_mfma_i32_16x16x64_i8 v[54:57], v[18:21], v[178:181], v[54:57]
	v_mfma_i32_16x16x64_i8 v[54:57], v[22:25], v[182:185], v[54:57]
	v_mfma_i32_16x16x64_i8 v[30:33], v[38:41], v[182:185], v[30:33]
	v_mfma_i32_16x16x64_i8 v[30:33], v[34:37], v[178:181], v[30:33]
	v_mfma_i32_16x16x64_i8 v[58:61], v[34:37], v[186:189], v[58:61]
	v_mfma_i32_16x16x64_i8 v[58:61], v[38:41], v[190:193], v[58:61]
	v_mfma_i32_16x16x64_i8 v[94:97], v[22:25], v[190:193], v[94:97]
	v_mfma_i32_16x16x64_i8 v[94:97], v[18:21], v[186:189], v[94:97]
	v_mfma_i32_16x16x64_i8 v[62:65], v[154:157], v[186:189], v[62:65]
	v_mfma_i32_16x16x64_i8 v[62:65], v[158:161], v[190:193], v[62:65]
	v_mfma_i32_16x16x64_i8 v[138:141], v[158:161], v[166:169], v[138:141]
	v_mfma_i32_16x16x64_i8 v[138:141], v[154:157], v[162:165], v[138:141]
	v_mfma_i32_16x16x64_i8 v[142:145], v[130:133], v[162:165], v[142:145]
	v_mfma_i32_16x16x64_i8 v[142:145], v[134:137], v[166:169], v[142:145]
	v_mfma_i32_16x16x64_i8 v[102:105], v[134:137], v[174:177], v[102:105]
	v_mfma_i32_16x16x64_i8 v[102:105], v[130:133], v[170:173], v[102:105]
	v_mfma_i32_16x16x64_i8 v[98:101], v[154:157], v[170:173], v[98:101]
	v_mfma_i32_16x16x64_i8 v[98:101], v[158:161], v[174:177], v[98:101]
	v_mfma_i32_16x16x64_i8 v[26:29], v[158:161], v[182:185], v[26:29]
	v_mfma_i32_16x16x64_i8 v[26:29], v[154:157], v[178:181], v[26:29]
	v_mfma_i32_16x16x64_i8 v[42:45], v[130:133], v[178:181], v[42:45]
	v_mfma_i32_16x16x64_i8 v[42:45], v[134:137], v[182:185], v[42:45]
	v_mfma_i32_16x16x64_i8 v[78:81], v[134:137], v[190:193], v[78:81]
	v_mfma_i32_16x16x64_i8 v[78:81], v[130:133], v[186:189], v[78:81]
	s_barrier
	s_add_i32 s0, vcc_hi, s69
	s_mov_b32 m0, s0
	ds_read_b128 v[162:165], v243 offset:16384
	ds_read_b128 v[166:169], v243 offset:17408
	ds_read_b128 v[170:173], v243 offset:18432
	ds_read_b128 v[174:177], v243 offset:19456
	ds_read_b128 v[178:181], v243 offset:20480
	ds_read_b128 v[182:185], v243 offset:21504
	ds_read_b128 v[186:189], v243 offset:22528
	ds_read_b128 v[190:193], v243 offset:23552
	global_load_lds_dwordx4 v0, s[6:7]
	s_add_i32 m0, s0, 0x2000
	s_add_u32 s0, s6, 0x40000
	s_addc_u32 s1, s7, 0
	s_add_i32 s4, s4, s69
	global_load_lds_dwordx4 v214, s[6:7]
	s_mov_b32 m0, s4
	s_nop 0
	global_load_lds_dwordx4 v0, s[0:1]
	s_add_i32 m0, s4, 0x2000
	s_nop 0
	global_load_lds_dwordx4 v214, s[0:1]
	s_mov_b32 m0, s11
	s_nop 0
	global_load_lds_dwordx4 v210, s[12:13]
	s_mov_b32 m0, s71
	s_nop 0
	global_load_lds_dwordx4 v212, s[12:13]
	s_waitcnt vmcnt(8)
	s_waitcnt lgkmcnt(0)
	s_barrier
	s_waitcnt lgkmcnt(0)
	v_mfma_i32_16x16x64_i8 v[106:109], v[18:21], v[162:165], v[106:109]
	v_mfma_i32_16x16x64_i8 v[106:109], v[22:25], v[166:169], v[106:109]
	v_mfma_i32_16x16x64_i8 v[46:49], v[34:37], v[162:165], v[46:49]
	v_mfma_i32_16x16x64_i8 v[46:49], v[38:41], v[166:169], v[46:49]
	v_mfma_i32_16x16x64_i8 v[6:9], v[34:37], v[170:173], v[6:9]
	v_mfma_i32_16x16x64_i8 v[6:9], v[38:41], v[174:177], v[6:9]
	v_mfma_i32_16x16x64_i8 v[14:17], v[18:21], v[170:173], v[14:17]
	v_mfma_i32_16x16x64_i8 v[14:17], v[22:25], v[174:177], v[14:17]
	v_mfma_i32_16x16x64_i8 v[90:93], v[18:21], v[178:181], v[90:93]
	v_mfma_i32_16x16x64_i8 v[90:93], v[22:25], v[182:185], v[90:93]
	v_mfma_i32_16x16x64_i8 v[86:89], v[34:37], v[178:181], v[86:89]
	v_mfma_i32_16x16x64_i8 v[86:89], v[38:41], v[182:185], v[86:89]
	v_mfma_i32_16x16x64_i8 v[18:21], v[18:21], v[186:189], v[126:129]
	v_mfma_i32_16x16x64_i8 v[18:21], v[22:25], v[190:193], v[18:21]
	v_mfma_i32_16x16x64_i8 v[22:25], v[34:37], v[186:189], v[66:69]
	v_mfma_i32_16x16x64_i8 v[22:25], v[38:41], v[190:193], v[22:25]
	v_mfma_i32_16x16x64_i8 v[38:41], v[154:157], v[162:165], v[50:53]
	v_mfma_i32_16x16x64_i8 v[38:41], v[158:161], v[166:169], v[38:41]
	v_mfma_i32_16x16x64_i8 v[2:5], v[154:157], v[170:173], v[2:5]
	v_mfma_i32_16x16x64_i8 v[2:5], v[158:161], v[174:177], v[2:5]
	v_mfma_i32_16x16x64_i8 v[10:13], v[130:133], v[170:173], v[10:13]
	v_mfma_i32_16x16x64_i8 v[10:13], v[134:137], v[174:177], v[10:13]
	v_mfma_i32_16x16x64_i8 v[50:53], v[130:133], v[178:181], v[82:85]
	v_mfma_i32_16x16x64_i8 v[82:85], v[134:137], v[182:185], v[50:53]
	v_mfma_i32_16x16x64_i8 v[34:37], v[130:133], v[162:165], v[114:117]
	v_mfma_i32_16x16x64_i8 v[34:37], v[134:137], v[166:169], v[34:37]
	v_mfma_i32_16x16x64_i8 v[50:53], v[154:157], v[178:181], v[74:77]
	v_mfma_i32_16x16x64_i8 v[74:77], v[158:161], v[182:185], v[50:53]
	v_mfma_i32_16x16x64_i8 v[50:53], v[130:133], v[186:189], v[122:125]
	v_mfma_i32_16x16x64_i8 v[122:125], v[134:137], v[190:193], v[50:53]
	v_mfma_i32_16x16x64_i8 v[50:53], v[154:157], v[186:189], v[70:73]
	v_mfma_i32_16x16x64_i8 v[70:73], v[158:161], v[190:193], v[50:53]
	s_barrier
; #define PG8_STAGE(bufoff, gbase, voff) do { _Pragma("unroll") for (int _i = 0; _i < 2; ++_i) \
;         __builtin_amdgcn_global_load_lds((const unsigned*)((const char*)(gbase) + (voff)[_i]), (PG8_LAS unsigned*)(lds + (bufoff) + ldsw + _i * 8192), 16, 0, 0); } while (0)
; #define PG8_LDA(dst, b, h) do { _Pragma("unroll") for (int m = 0; m < 4; ++m) _Pragma("unroll") for (int k = 0; k < 2; ++k) dst[m][k] = *(const PG8_LAS bf16x8*)(lds + PG8_SA(b, h) + aoff + m * 2048 + k * 1024); } while (0)
; #define PG8_LDB(dst, b, h) do { _Pragma("unroll") for (int n = 0; n < 2; ++n) _Pragma("unroll") for (int k = 0; k < 2; ++k) dst[n][k] = *(const PG8_LAS bf16x8*)(lds + PG8_SB(b, h) + boff + n * 2048 + k * 1024); } while (0)
; #define PG8_MMA(ai, bj, At, Bt) do { __builtin_amdgcn_s_setprio(1); _Pragma("unroll") for (int m = 0; m < 4; ++m) _Pragma("unroll") for (int n = 0; n < 2; ++n) _Pragma("unroll") for (int k = 0; k < 2; ++k) \
;         acc[ai][bj][m][n] = mma16<Epi::I8>(Bt[n][k], At[m][k], acc[ai][bj][m][n]); __builtin_amdgcn_s_setprio(0); } while (0)
; #define PG8_WAIT_V(n) asm volatile("s_waitcnt vmcnt(" #n ")" ::: "memory")
; #define PG8_WAIT_L(n) asm volatile("s_waitcnt lgkmcnt(" #n ")" ::: "memory")
; #define PG8_BAR __builtin_amdgcn_s_barrier()
; #define PG8_SCHED __builtin_amdgcn_sched_barrier(0)
; template <class Epi, class Sched, bool ALIGN_EPI = false, bool SP2 = false>
; __device__ __forceinline__ void gemm_phase(PG8_LAS unsigned char* lds, const Gemm g, const Sched& S, const Epi& E) {
;     ...
;             PG8_LDB(B0, 1, 0); PG8_LDB(B1, 1, 1); PG8_SCHED; PG8_LDA(At, 1, 0); PG8_STAGE(PG8_SA(0, 1), a2 + hstep, voffA);
;             PG8_WAIT_V(8); PG8_WAIT_L(0); PG8_BAR; PG8_MMA(0, 0, At, B0); PG8_MMA(0, 1, At, B1); PG8_BAR; PG8_SCHED;
;             PG8_LDA(At, 1, 1); PG8_STAGE(PG8_SB(1, 0), b3, voffB); PG8_STAGE(PG8_SB(1, 1), b3 + hstep, voffB); PG8_STAGE(PG8_SA(1, 0), a3, voffA);
;             PG8_WAIT_V(8); PG8_WAIT_L(0); PG8_BAR; PG8_MMA(1, 0, At, B0); PG8_MMA(1, 1, At, B1); PG8_BAR; PG8_SCHED;
	s_add_i32 s4, 0, 0x18000
	v_add_u32_e32 v126, s4, v242
	s_add_i32 s5, 0, 0x1c000
	ds_read_b128 v[50:53], v126
	ds_read_b128 v[66:69], v126 offset:1024
	ds_read_b128 v[114:117], v126 offset:2048
	ds_read_b128 v[130:133], v126 offset:3072
	v_add_u32_e32 v126, s5, v242
	ds_read_b128 v[134:137], v126
	ds_read_b128 v[154:157], v126 offset:1024
	ds_read_b128 v[158:161], v126 offset:2048
	ds_read_b128 v[162:165], v126 offset:3072
	s_add_u32 s0, s12, 0x40000
	s_addc_u32 s1, s13, 0
	s_mov_b32 m0, s80
	ds_read_b128 v[126:129], v243 offset:32768
	ds_read_b128 v[166:169], v243 offset:33792
	ds_read_b128 v[170:173], v243 offset:34816
	ds_read_b128 v[174:177], v243 offset:35840
	ds_read_b128 v[178:181], v243 offset:36864
	ds_read_b128 v[182:185], v243 offset:37888
	ds_read_b128 v[186:189], v243 offset:38912
	ds_read_b128 v[190:193], v243 offset:39936
	global_load_lds_dwordx4 v210, s[0:1]
	s_mov_b32 m0, s81
	s_nop 0
	global_load_lds_dwordx4 v212, s[0:1]
	s_waitcnt vmcnt(8)
	s_waitcnt lgkmcnt(0)
	s_barrier
	s_waitcnt lgkmcnt(0)
	v_mfma_i32_16x16x64_i8 v[150:153], v[50:53], v[126:129], v[150:153]
	v_mfma_i32_16x16x64_i8 v[150:153], v[66:69], v[166:169], v[150:153]
	v_mfma_i32_16x16x64_i8 v[146:149], v[114:117], v[126:129], v[146:149]
	v_mfma_i32_16x16x64_i8 v[146:149], v[130:133], v[166:169], v[146:149]
	v_mfma_i32_16x16x64_i8 v[110:113], v[114:117], v[170:173], v[110:113]
	v_mfma_i32_16x16x64_i8 v[110:113], v[130:133], v[174:177], v[110:113]
	v_mfma_i32_16x16x64_i8 v[118:121], v[50:53], v[170:173], v[118:121]
	v_mfma_i32_16x16x64_i8 v[118:121], v[66:69], v[174:177], v[118:121]
	v_mfma_i32_16x16x64_i8 v[54:57], v[50:53], v[178:181], v[54:57]
	v_mfma_i32_16x16x64_i8 v[54:57], v[66:69], v[182:185], v[54:57]
	v_mfma_i32_16x16x64_i8 v[30:33], v[114:117], v[178:181], v[30:33]
	v_mfma_i32_16x16x64_i8 v[30:33], v[130:133], v[182:185], v[30:33]
	v_mfma_i32_16x16x64_i8 v[58:61], v[114:117], v[186:189], v[58:61]
	v_mfma_i32_16x16x64_i8 v[58:61], v[130:133], v[190:193], v[58:61]
	v_mfma_i32_16x16x64_i8 v[94:97], v[50:53], v[186:189], v[94:97]
	v_mfma_i32_16x16x64_i8 v[94:97], v[66:69], v[190:193], v[94:97]
	v_mfma_i32_16x16x64_i8 v[142:145], v[134:137], v[126:129], v[142:145]
	v_mfma_i32_16x16x64_i8 v[142:145], v[154:157], v[166:169], v[142:145]
	v_mfma_i32_16x16x64_i8 v[126:129], v[158:161], v[126:129], v[138:141]
	v_mfma_i32_16x16x64_i8 v[138:141], v[162:165], v[166:169], v[126:129]
	v_mfma_i32_16x16x64_i8 v[98:101], v[158:161], v[170:173], v[98:101]
	v_mfma_i32_16x16x64_i8 v[98:101], v[162:165], v[174:177], v[98:101]
	v_mfma_i32_16x16x64_i8 v[102:105], v[134:137], v[170:173], v[102:105]
	v_mfma_i32_16x16x64_i8 v[102:105], v[154:157], v[174:177], v[102:105]
	v_mfma_i32_16x16x64_i8 v[42:45], v[134:137], v[178:181], v[42:45]
	v_mfma_i32_16x16x64_i8 v[42:45], v[154:157], v[182:185], v[42:45]
	v_mfma_i32_16x16x64_i8 v[26:29], v[158:161], v[178:181], v[26:29]
	v_mfma_i32_16x16x64_i8 v[26:29], v[162:165], v[182:185], v[26:29]
	v_mfma_i32_16x16x64_i8 v[62:65], v[158:161], v[186:189], v[62:65]
	v_mfma_i32_16x16x64_i8 v[62:65], v[162:165], v[190:193], v[62:65]
	v_mfma_i32_16x16x64_i8 v[78:81], v[134:137], v[186:189], v[78:81]
	v_mfma_i32_16x16x64_i8 v[78:81], v[154:157], v[190:193], v[78:81]
	s_barrier
	s_add_u32 s98, s6, 0x80
	s_addc_u32 s99, s7, 0
	s_add_u32 s100, s12, 0x80
	s_addc_u32 s101, s13, 0
	s_add_i32 s0, s4, s69
	s_mov_b32 m0, s0
	ds_read_b128 v[166:169], v243 offset:49152
	ds_read_b128 v[170:173], v243 offset:50176
	ds_read_b128 v[174:177], v243 offset:51200
	ds_read_b128 v[178:181], v243 offset:52224
	ds_read_b128 v[182:185], v243 offset:53248
	ds_read_b128 v[186:189], v243 offset:54272
	ds_read_b128 v[190:193], v243 offset:55296
	ds_read_b128 v[194:197], v243 offset:56320
	global_load_lds_dwordx4 v0, s[98:99]
	s_add_i32 m0, s0, 0x2000
	s_add_u32 s0, s6, 0x40080
	s_addc_u32 s1, s7, 0
	s_add_i32 s4, s5, s69
	global_load_lds_dwordx4 v214, s[98:99]
	s_mov_b32 m0, s4
	s_nop 0
	global_load_lds_dwordx4 v0, s[0:1]
	s_add_i32 m0, s4, 0x2000
	s_nop 0
	global_load_lds_dwordx4 v214, s[0:1]
	s_mov_b32 m0, s84
	s_nop 0
	global_load_lds_dwordx4 v210, s[100:101]
	s_mov_b32 m0, s85
	s_nop 0
	global_load_lds_dwordx4 v212, s[100:101]
	s_waitcnt vmcnt(8)
	s_waitcnt lgkmcnt(0)
	s_barrier
	s_waitcnt lgkmcnt(0)
	v_mfma_i32_16x16x64_i8 v[18:21], v[50:53], v[190:193], v[18:21]
	v_mfma_i32_16x16x64_i8 v[126:129], v[66:69], v[194:197], v[18:21]
	v_mfma_i32_16x16x64_i8 v[106:109], v[50:53], v[166:169], v[106:109]
	v_mfma_i32_16x16x64_i8 v[106:109], v[66:69], v[170:173], v[106:109]
	v_mfma_i32_16x16x64_i8 v[46:49], v[114:117], v[166:169], v[46:49]
	v_mfma_i32_16x16x64_i8 v[46:49], v[130:133], v[170:173], v[46:49]
	v_mfma_i32_16x16x64_i8 v[6:9], v[114:117], v[174:177], v[6:9]
	v_mfma_i32_16x16x64_i8 v[6:9], v[130:133], v[178:181], v[6:9]
	v_mfma_i32_16x16x64_i8 v[14:17], v[50:53], v[174:177], v[14:17]
	v_mfma_i32_16x16x64_i8 v[14:17], v[66:69], v[178:181], v[14:17]
	v_mfma_i32_16x16x64_i8 v[90:93], v[50:53], v[182:185], v[90:93]
	v_mfma_i32_16x16x64_i8 v[90:93], v[66:69], v[186:189], v[90:93]
	v_mfma_i32_16x16x64_i8 v[86:89], v[114:117], v[182:185], v[86:89]
	v_mfma_i32_16x16x64_i8 v[86:89], v[130:133], v[186:189], v[86:89]
	v_mfma_i32_16x16x64_i8 v[18:21], v[114:117], v[190:193], v[22:25]
	v_mfma_i32_16x16x64_i8 v[66:69], v[130:133], v[194:197], v[18:21]
	v_mfma_i32_16x16x64_i8 v[18:21], v[134:137], v[166:169], v[34:37]
	v_mfma_i32_16x16x64_i8 v[114:117], v[154:157], v[170:173], v[18:21]
	v_mfma_i32_16x16x64_i8 v[10:13], v[134:137], v[174:177], v[10:13]
	v_mfma_i32_16x16x64_i8 v[10:13], v[154:157], v[178:181], v[10:13]
	v_mfma_i32_16x16x64_i8 v[2:5], v[158:161], v[174:177], v[2:5]
	v_mfma_i32_16x16x64_i8 v[2:5], v[162:165], v[178:181], v[2:5]
	v_mfma_i32_16x16x64_i8 v[18:21], v[158:161], v[166:169], v[38:41]
	v_mfma_i32_16x16x64_i8 v[50:53], v[162:165], v[170:173], v[18:21]
	v_mfma_i32_16x16x64_i8 v[18:21], v[134:137], v[182:185], v[82:85]
	v_mfma_i32_16x16x64_i8 v[82:85], v[154:157], v[186:189], v[18:21]
	v_mfma_i32_16x16x64_i8 v[18:21], v[158:161], v[182:185], v[74:77]
	v_mfma_i32_16x16x64_i8 v[74:77], v[162:165], v[186:189], v[18:21]
	v_mfma_i32_16x16x64_i8 v[18:21], v[134:137], v[190:193], v[122:125]
	v_mfma_i32_16x16x64_i8 v[122:125], v[154:157], v[194:197], v[18:21]
	v_mfma_i32_16x16x64_i8 v[18:21], v[158:161], v[190:193], v[70:73]
	v_mfma_i32_16x16x64_i8 v[70:73], v[162:165], v[194:197], v[18:21]
	s_barrier
	s_add_i32 vcc_lo, vcc_lo, 2
	s_add_u32 s96, s96, 0x100
	s_addc_u32 s97, s97, 0
	s_cmp_gt_u32 vcc_lo, 13
	s_mov_b64 s[0:1], s[8:9]
	s_cbranch_scc0 .LBB0_80

; #define PG8_STAGE(bufoff, gbase, voff) do { _Pragma("unroll") for (int _i = 0; _i < 2; ++_i) \
;         __builtin_amdgcn_global_load_lds((const unsigned*)((const char*)(gbase) + (voff)[_i]), (PG8_LAS unsigned*)(lds + (bufoff) + ldsw + _i * 8192), 16, 0, 0); } while (0)
; #define PG8_LDA(dst, b, h) do { _Pragma("unroll") for (int m = 0; m < 4; ++m) _Pragma("unroll") for (int k = 0; k < 2; ++k) dst[m][k] = *(const PG8_LAS bf16x8*)(lds + PG8_SA(b, h) + aoff + m * 2048 + k * 1024); } while (0)
; #define PG8_LDB(dst, b, h) do { _Pragma("unroll") for (int n = 0; n < 2; ++n) _Pragma("unroll") for (int k = 0; k < 2; ++k) dst[n][k] = *(const PG8_LAS bf16x8*)(lds + PG8_SB(b, h) + boff + n * 2048 + k * 1024); } while (0)
; #define PG8_MMA(ai, bj, At, Bt) do { __builtin_amdgcn_s_setprio(1); _Pragma("unroll") for (int m = 0; m < 4; ++m) _Pragma("unroll") for (int n = 0; n < 2; ++n) _Pragma("unroll") for (int k = 0; k < 2; ++k) \
;         acc[ai][bj][m][n] = mma16<Epi::I8>(Bt[n][k], At[m][k], acc[ai][bj][m][n]); __builtin_amdgcn_s_setprio(0); } while (0)
; #define PG8_WAIT_V(n) asm volatile("s_waitcnt vmcnt(" #n ")" ::: "memory")
; #define PG8_WAIT_L(n) asm volatile("s_waitcnt lgkmcnt(" #n ")" ::: "memory")
; #define PG8_BAR __builtin_amdgcn_s_barrier()
; template <class Epi, class Sched, bool ALIGN_EPI = false, bool SP2 = false>
; __device__ __forceinline__ void gemm_phase(PG8_LAS unsigned char* lds, const Gemm g, const Sched& S, const Epi& E) {
;     ...
;             const bool last = (t == nt - 2);
;             const char* a1 = cA + (size_t)(t + 1) * kstep;
;             const char* a2 = last ? nA : cA + (size_t)(t + 2) * kstep; const char* b2 = last ? nB : cB + (size_t)(t + 2) * kstep;
;             const char* a3 = a2 + kstep; const char* b3 = b2 + kstep;
;             if (last && has_next) S.a_ready(nxt);
;             if constexpr (SP2) {
;             PG8_LDB(B0, 0, 0); PG8_LDB(B1, 0, 1); PG8_SCHED; PG8_LDA(At, 0, 0); PG8_STAGE(PG8_SA(1, 1), a1 + hstep, voffA);
;             PG8_WAIT_V(8); PG8_WAIT_L(0); PG8_BAR; PG8_MMA(0, 0, At, B0); PG8_MMA(0, 1, At, B1); PG8_BAR; PG8_SCHED;
;             PG8_LDA(At, 0, 1); PG8_STAGE(PG8_SB(0, 0), b2, voffB); PG8_STAGE(PG8_SB(0, 1), b2 + hstep, voffB); PG8_STAGE(PG8_SA(0, 0), a2, voffA);
;             PG8_WAIT_V(8); PG8_WAIT_L(0); PG8_BAR; PG8_MMA(1, 0, At, B0); PG8_MMA(1, 1, At, B1); PG8_BAR; PG8_SCHED;
.Lpeel291:
	s_add_u32 s84, s8, 0x100
	s_addc_u32 s85, s9, 0
	s_add_i32 s66, 0, 0x10000
	s_cmp_eq_u32 s10, 12
	s_cselect_b32 vcc_hi, s5, s85
	s_cselect_b32 vcc_lo, s7, s84
	s_cselect_b32 s97, s11, s68
	s_cselect_b32 s96, s67, s69
	s_add_i32 s70, 0, 0x14000
	v_add_u32_e32 v110, s66, v175
	v_add_u32_e32 v168, s70, v175
	s_waitcnt vmcnt(0)
	ds_read_b128 v[66:69], v110
	ds_read_b128 v[70:73], v110 offset:1024
	ds_read_b128 v[106:109], v110 offset:2048
	ds_read_b128 v[110:113], v110 offset:3072
	ds_read_b128 v[114:117], v168
	ds_read_b128 v[118:121], v168 offset:1024
	ds_read_b128 v[126:129], v168 offset:2048
	ds_read_b128 v[178:181], v168 offset:3072
	s_add_i32 m0, s1, 0xc000
	ds_read_b128 v[182:185], v177
	ds_read_b128 v[186:189], v177 offset:1024
	ds_read_b128 v[190:193], v177 offset:2048
	ds_read_b128 v[194:197], v177 offset:3072
	ds_read_b128 v[198:201], v177 offset:4096
	ds_read_b128 v[210:213], v177 offset:5120
	ds_read_b128 v[214:217], v177 offset:6144
	ds_read_b128 v[218:221], v177 offset:7168
	global_load_lds_dwordx4 v164, s[8:9]
	s_add_i32 m0, s1, 0xe000
	s_nop 0
	global_load_lds_dwordx4 v166, s[8:9]
	s_waitcnt vmcnt(8)
	s_waitcnt lgkmcnt(0)
	s_barrier
	s_waitcnt lgkmcnt(0)
	v_mfma_i32_16x16x64_i8 v[154:157], v[66:69], v[182:185], 0
	v_mfma_i32_16x16x64_i8 v[154:157], v[70:73], v[186:189], v[154:157]
	v_mfma_i32_16x16x64_i8 v[146:149], v[110:113], v[186:189], 0
	v_mfma_i32_16x16x64_i8 v[146:149], v[106:109], v[182:185], v[146:149]
	v_mfma_i32_16x16x64_i8 v[138:141], v[106:109], v[190:193], 0
	v_mfma_i32_16x16x64_i8 v[138:141], v[110:113], v[194:197], v[138:141]
	v_mfma_i32_16x16x64_i8 v[150:153], v[70:73], v[194:197], 0
	v_mfma_i32_16x16x64_i8 v[150:153], v[66:69], v[190:193], v[150:153]
	v_mfma_i32_16x16x64_i8 v[142:145], v[66:69], v[198:201], 0
	v_mfma_i32_16x16x64_i8 v[142:145], v[70:73], v[210:213], v[142:145]
	v_mfma_i32_16x16x64_i8 v[130:133], v[110:113], v[210:213], 0
	v_mfma_i32_16x16x64_i8 v[130:133], v[106:109], v[198:201], v[130:133]
	v_mfma_i32_16x16x64_i8 v[122:125], v[106:109], v[214:217], 0
	v_mfma_i32_16x16x64_i8 v[122:125], v[110:113], v[218:221], v[122:125]
	v_mfma_i32_16x16x64_i8 v[134:137], v[70:73], v[218:221], 0
	v_mfma_i32_16x16x64_i8 v[134:137], v[66:69], v[214:217], v[134:137]
	v_mfma_i32_16x16x64_i8 v[74:77], v[126:129], v[214:217], 0
	v_mfma_i32_16x16x64_i8 v[74:77], v[178:181], v[218:221], v[74:77]
	v_mfma_i32_16x16x64_i8 v[94:97], v[178:181], v[186:189], 0
	v_mfma_i32_16x16x64_i8 v[94:97], v[126:129], v[182:185], v[94:97]
	v_mfma_i32_16x16x64_i8 v[102:105], v[114:117], v[182:185], 0
	v_mfma_i32_16x16x64_i8 v[102:105], v[118:121], v[186:189], v[102:105]
	v_mfma_i32_16x16x64_i8 v[98:101], v[118:121], v[194:197], 0
	v_mfma_i32_16x16x64_i8 v[98:101], v[114:117], v[190:193], v[98:101]
	v_mfma_i32_16x16x64_i8 v[86:89], v[126:129], v[190:193], 0
	v_mfma_i32_16x16x64_i8 v[86:89], v[178:181], v[194:197], v[86:89]
	v_mfma_i32_16x16x64_i8 v[78:81], v[178:181], v[210:213], 0
	v_mfma_i32_16x16x64_i8 v[78:81], v[126:129], v[198:201], v[78:81]
	v_mfma_i32_16x16x64_i8 v[90:93], v[114:117], v[198:201], 0
	v_mfma_i32_16x16x64_i8 v[90:93], v[118:121], v[210:213], v[90:93]
	v_mfma_i32_16x16x64_i8 v[82:85], v[118:121], v[218:221], 0
	v_mfma_i32_16x16x64_i8 v[82:85], v[114:117], v[214:217], v[82:85]
	s_barrier
	s_add_i32 s8, s66, s81
	s_mov_b32 m0, s8
	ds_read_b128 v[182:185], v177 offset:16384
	ds_read_b128 v[186:189], v177 offset:17408
	ds_read_b128 v[190:193], v177 offset:18432
	ds_read_b128 v[194:197], v177 offset:19456
	ds_read_b128 v[198:201], v177 offset:20480
	ds_read_b128 v[210:213], v177 offset:21504
	ds_read_b128 v[214:217], v177 offset:22528
	ds_read_b128 v[218:221], v177 offset:23552
	global_load_lds_dwordx4 v0, s[96:97]
	s_add_i32 m0, s8, 0x2000
	s_add_u32 s8, s96, 0x40000
	s_addc_u32 s9, s97, 0
	s_add_i32 s66, s70, s81
	global_load_lds_dwordx4 v158, s[96:97]
	s_mov_b32 m0, s66
	s_nop 0
	global_load_lds_dwordx4 v0, s[8:9]
	s_add_i32 m0, s66, 0x2000
	s_nop 0
	global_load_lds_dwordx4 v158, s[8:9]
	s_mov_b32 m0, s1
	s_nop 0
	global_load_lds_dwordx4 v162, vcc
	s_mov_b32 m0, s58
	s_nop 0
	global_load_lds_dwordx4 v160, vcc
	s_waitcnt vmcnt(8)
	s_waitcnt lgkmcnt(0)
	s_barrier
	s_waitcnt lgkmcnt(0)
	v_mfma_i32_16x16x64_i8 v[62:65], v[66:69], v[182:185], 0
	v_mfma_i32_16x16x64_i8 v[62:65], v[70:73], v[186:189], v[62:65]
	v_mfma_i32_16x16x64_i8 v[54:57], v[110:113], v[186:189], 0
	v_mfma_i32_16x16x64_i8 v[54:57], v[106:109], v[182:185], v[54:57]
	v_mfma_i32_16x16x64_i8 v[46:49], v[106:109], v[190:193], 0
	v_mfma_i32_16x16x64_i8 v[46:49], v[110:113], v[194:197], v[46:49]
	v_mfma_i32_16x16x64_i8 v[58:61], v[70:73], v[194:197], 0
	v_mfma_i32_16x16x64_i8 v[58:61], v[66:69], v[190:193], v[58:61]
	v_mfma_i32_16x16x64_i8 v[50:53], v[66:69], v[198:201], 0
	v_mfma_i32_16x16x64_i8 v[50:53], v[70:73], v[210:213], v[50:53]
	v_mfma_i32_16x16x64_i8 v[38:41], v[110:113], v[210:213], 0
	v_mfma_i32_16x16x64_i8 v[38:41], v[106:109], v[198:201], v[38:41]
	v_mfma_i32_16x16x64_i8 v[34:37], v[106:109], v[214:217], 0
	v_mfma_i32_16x16x64_i8 v[34:37], v[110:113], v[218:221], v[34:37]
	v_mfma_i32_16x16x64_i8 v[42:45], v[70:73], v[218:221], 0
	v_mfma_i32_16x16x64_i8 v[42:45], v[66:69], v[214:217], v[42:45]
	v_mfma_i32_16x16x64_i8 v[2:5], v[126:129], v[214:217], 0
	v_mfma_i32_16x16x64_i8 v[2:5], v[178:181], v[218:221], v[2:5]
	v_mfma_i32_16x16x64_i8 v[22:25], v[178:181], v[186:189], 0
	v_mfma_i32_16x16x64_i8 v[22:25], v[126:129], v[182:185], v[22:25]
	v_mfma_i32_16x16x64_i8 v[30:33], v[114:117], v[182:185], 0
	v_mfma_i32_16x16x64_i8 v[30:33], v[118:121], v[186:189], v[30:33]
	v_mfma_i32_16x16x64_i8 v[26:29], v[118:121], v[194:197], 0
	v_mfma_i32_16x16x64_i8 v[26:29], v[114:117], v[190:193], v[26:29]
	v_mfma_i32_16x16x64_i8 v[14:17], v[126:129], v[190:193], 0
	v_mfma_i32_16x16x64_i8 v[14:17], v[178:181], v[194:197], v[14:17]
	v_mfma_i32_16x16x64_i8 v[6:9], v[178:181], v[210:213], 0
	v_mfma_i32_16x16x64_i8 v[6:9], v[126:129], v[198:201], v[6:9]
	v_mfma_i32_16x16x64_i8 v[18:21], v[114:117], v[198:201], 0
	v_mfma_i32_16x16x64_i8 v[18:21], v[118:121], v[210:213], v[18:21]
	v_mfma_i32_16x16x64_i8 v[10:13], v[118:121], v[218:221], 0
	v_mfma_i32_16x16x64_i8 v[10:13], v[114:117], v[214:217], v[10:13]
	s_barrier
; #define PG8_STAGE(bufoff, gbase, voff) do { _Pragma("unroll") for (int _i = 0; _i < 2; ++_i) \
;         __builtin_amdgcn_global_load_lds((const unsigned*)((const char*)(gbase) + (voff)[_i]), (PG8_LAS unsigned*)(lds + (bufoff) + ldsw + _i * 8192), 16, 0, 0); } while (0)
; #define PG8_LDA(dst, b, h) do { _Pragma("unroll") for (int m = 0; m < 4; ++m) _Pragma("unroll") for (int k = 0; k < 2; ++k) dst[m][k] = *(const PG8_LAS bf16x8*)(lds + PG8_SA(b, h) + aoff + m * 2048 + k * 1024); } while (0)
; #define PG8_LDB(dst, b, h) do { _Pragma("unroll") for (int n = 0; n < 2; ++n) _Pragma("unroll") for (int k = 0; k < 2; ++k) dst[n][k] = *(const PG8_LAS bf16x8*)(lds + PG8_SB(b, h) + boff + n * 2048 + k * 1024); } while (0)
; #define PG8_MMA(ai, bj, At, Bt) do { __builtin_amdgcn_s_setprio(1); _Pragma("unroll") for (int m = 0; m < 4; ++m) _Pragma("unroll") for (int n = 0; n < 2; ++n) _Pragma("unroll") for (int k = 0; k < 2; ++k) \
;         acc[ai][bj][m][n] = mma16<Epi::I8>(Bt[n][k], At[m][k], acc[ai][bj][m][n]); __builtin_amdgcn_s_setprio(0); } while (0)
; #define PG8_WAIT_V(n) asm volatile("s_waitcnt vmcnt(" #n ")" ::: "memory")
; #define PG8_WAIT_L(n) asm volatile("s_waitcnt lgkmcnt(" #n ")" ::: "memory")
; #define PG8_BAR __builtin_amdgcn_s_barrier()
; #define PG8_SCHED __builtin_amdgcn_sched_barrier(0)
; template <class Epi, class Sched, bool ALIGN_EPI = false, bool SP2 = false>
; __device__ __forceinline__ void gemm_phase(PG8_LAS unsigned char* lds, const Gemm g, const Sched& S, const Epi& E) {
;     ...
;             PG8_LDB(B0, 1, 0); PG8_LDB(B1, 1, 1); PG8_SCHED; PG8_LDA(At, 1, 0); PG8_STAGE(PG8_SA(0, 1), a2 + hstep, voffA);
;             PG8_WAIT_V(8); PG8_WAIT_L(0); PG8_BAR; PG8_MMA(0, 0, At, B0); PG8_MMA(0, 1, At, B1); PG8_BAR; PG8_SCHED;
;             PG8_LDA(At, 1, 1); PG8_STAGE(PG8_SB(1, 0), b3, voffB); PG8_STAGE(PG8_SB(1, 1), b3 + hstep, voffB); PG8_STAGE(PG8_SA(1, 0), a3, voffA);
;             PG8_WAIT_V(8); PG8_WAIT_L(0); PG8_BAR; PG8_MMA(1, 0, At, B0); PG8_MMA(1, 1, At, B1); PG8_BAR; PG8_SCHED;
	s_add_i32 s66, 0, 0x18000
	s_add_i32 s70, 0, 0x1c000
	v_add_u32_e32 v110, s66, v175
	v_add_u32_e32 v170, s70, v175
	ds_read_b128 v[66:69], v110
	ds_read_b128 v[70:73], v110 offset:1024
	ds_read_b128 v[106:109], v110 offset:2048
	ds_read_b128 v[110:113], v110 offset:3072
	ds_read_b128 v[114:117], v170
	ds_read_b128 v[118:121], v170 offset:1024
	ds_read_b128 v[126:129], v170 offset:2048
	ds_read_b128 v[178:181], v170 offset:3072
	s_add_u32 s8, vcc_lo, 0x40000
	s_addc_u32 s9, vcc_hi, 0
	s_mov_b32 m0, s80
	ds_read_b128 v[182:185], v177 offset:32768
	ds_read_b128 v[186:189], v177 offset:33792
	ds_read_b128 v[190:193], v177 offset:34816
	ds_read_b128 v[194:197], v177 offset:35840
	ds_read_b128 v[198:201], v177 offset:36864
	ds_read_b128 v[210:213], v177 offset:37888
	ds_read_b128 v[214:217], v177 offset:38912
	ds_read_b128 v[218:221], v177 offset:39936
	global_load_lds_dwordx4 v162, s[8:9]
	s_mov_b32 m0, s0
	s_nop 0
	global_load_lds_dwordx4 v160, s[8:9]
	s_waitcnt vmcnt(8)
	s_waitcnt lgkmcnt(0)
	s_barrier
	s_waitcnt lgkmcnt(0)
	v_mfma_i32_16x16x64_i8 v[154:157], v[66:69], v[182:185], v[154:157]
	v_mfma_i32_16x16x64_i8 v[154:157], v[70:73], v[186:189], v[154:157]
	v_mfma_i32_16x16x64_i8 v[146:149], v[110:113], v[186:189], v[146:149]
	v_mfma_i32_16x16x64_i8 v[146:149], v[106:109], v[182:185], v[146:149]
	v_mfma_i32_16x16x64_i8 v[138:141], v[106:109], v[190:193], v[138:141]
	v_mfma_i32_16x16x64_i8 v[138:141], v[110:113], v[194:197], v[138:141]
	v_mfma_i32_16x16x64_i8 v[150:153], v[70:73], v[194:197], v[150:153]
	v_mfma_i32_16x16x64_i8 v[150:153], v[66:69], v[190:193], v[150:153]
	v_mfma_i32_16x16x64_i8 v[142:145], v[66:69], v[198:201], v[142:145]
	v_mfma_i32_16x16x64_i8 v[142:145], v[70:73], v[210:213], v[142:145]
	v_mfma_i32_16x16x64_i8 v[130:133], v[110:113], v[210:213], v[130:133]
	v_mfma_i32_16x16x64_i8 v[130:133], v[106:109], v[198:201], v[130:133]
	v_mfma_i32_16x16x64_i8 v[122:125], v[106:109], v[214:217], v[122:125]
	v_mfma_i32_16x16x64_i8 v[122:125], v[110:113], v[218:221], v[122:125]
	v_mfma_i32_16x16x64_i8 v[134:137], v[70:73], v[218:221], v[134:137]
	v_mfma_i32_16x16x64_i8 v[134:137], v[66:69], v[214:217], v[134:137]
	v_mfma_i32_16x16x64_i8 v[74:77], v[126:129], v[214:217], v[74:77]
	v_mfma_i32_16x16x64_i8 v[74:77], v[178:181], v[218:221], v[74:77]
	v_mfma_i32_16x16x64_i8 v[94:97], v[178:181], v[186:189], v[94:97]
	v_mfma_i32_16x16x64_i8 v[94:97], v[126:129], v[182:185], v[94:97]
	v_mfma_i32_16x16x64_i8 v[102:105], v[114:117], v[182:185], v[102:105]
	v_mfma_i32_16x16x64_i8 v[102:105], v[118:121], v[186:189], v[102:105]
	v_mfma_i32_16x16x64_i8 v[98:101], v[118:121], v[194:197], v[98:101]
	v_mfma_i32_16x16x64_i8 v[98:101], v[114:117], v[190:193], v[98:101]
	v_mfma_i32_16x16x64_i8 v[86:89], v[126:129], v[190:193], v[86:89]
	v_mfma_i32_16x16x64_i8 v[86:89], v[178:181], v[194:197], v[86:89]
	v_mfma_i32_16x16x64_i8 v[78:81], v[178:181], v[210:213], v[78:81]
	v_mfma_i32_16x16x64_i8 v[78:81], v[126:129], v[198:201], v[78:81]
	v_mfma_i32_16x16x64_i8 v[90:93], v[114:117], v[198:201], v[90:93]
	v_mfma_i32_16x16x64_i8 v[90:93], v[118:121], v[210:213], v[90:93]
	v_mfma_i32_16x16x64_i8 v[82:85], v[118:121], v[218:221], v[82:85]
	v_mfma_i32_16x16x64_i8 v[82:85], v[114:117], v[214:217], v[82:85]
	s_barrier
	s_add_i32 s8, s66, s81
	s_add_u32 s98, s96, 0x80
	s_addc_u32 s99, s97, 0
	s_add_u32 s100, vcc_lo, 0x80
	s_addc_u32 s101, vcc_hi, 0
	s_mov_b32 m0, s8
	ds_read_b128 v[182:185], v177 offset:49152
	ds_read_b128 v[186:189], v177 offset:50176
	ds_read_b128 v[190:193], v177 offset:51200
	ds_read_b128 v[194:197], v177 offset:52224
	ds_read_b128 v[198:201], v177 offset:53248
	ds_read_b128 v[210:213], v177 offset:54272
	ds_read_b128 v[214:217], v177 offset:55296
	ds_read_b128 v[218:221], v177 offset:56320
	global_load_lds_dwordx4 v0, s[98:99]
	s_add_i32 m0, s8, 0x2000
	s_add_u32 s8, s96, 0x40080
	s_addc_u32 s9, s97, 0
	s_add_i32 s66, s70, s81
	global_load_lds_dwordx4 v158, s[98:99]
	s_mov_b32 m0, s66
	s_nop 0
	global_load_lds_dwordx4 v0, s[8:9]
	s_add_i32 m0, s66, 0x2000
	s_nop 0
	global_load_lds_dwordx4 v158, s[8:9]
	s_mov_b32 m0, s13
	s_nop 0
	global_load_lds_dwordx4 v162, s[100:101]
	s_mov_b32 m0, s12
	s_nop 0
	global_load_lds_dwordx4 v160, s[100:101]
	s_waitcnt vmcnt(8)
	s_waitcnt lgkmcnt(0)
	s_barrier
	s_waitcnt lgkmcnt(0)
	v_mfma_i32_16x16x64_i8 v[62:65], v[66:69], v[182:185], v[62:65]
	v_mfma_i32_16x16x64_i8 v[62:65], v[70:73], v[186:189], v[62:65]
	v_mfma_i32_16x16x64_i8 v[54:57], v[110:113], v[186:189], v[54:57]
	v_mfma_i32_16x16x64_i8 v[54:57], v[106:109], v[182:185], v[54:57]
	v_mfma_i32_16x16x64_i8 v[46:49], v[106:109], v[190:193], v[46:49]
	v_mfma_i32_16x16x64_i8 v[46:49], v[110:113], v[194:197], v[46:49]
	v_mfma_i32_16x16x64_i8 v[58:61], v[70:73], v[194:197], v[58:61]
	v_mfma_i32_16x16x64_i8 v[58:61], v[66:69], v[190:193], v[58:61]
	v_mfma_i32_16x16x64_i8 v[50:53], v[66:69], v[198:201], v[50:53]
	v_mfma_i32_16x16x64_i8 v[50:53], v[70:73], v[210:213], v[50:53]
	v_mfma_i32_16x16x64_i8 v[38:41], v[110:113], v[210:213], v[38:41]
	v_mfma_i32_16x16x64_i8 v[38:41], v[106:109], v[198:201], v[38:41]
	v_mfma_i32_16x16x64_i8 v[34:37], v[106:109], v[214:217], v[34:37]
	v_mfma_i32_16x16x64_i8 v[34:37], v[110:113], v[218:221], v[34:37]
	v_mfma_i32_16x16x64_i8 v[42:45], v[70:73], v[218:221], v[42:45]
	v_mfma_i32_16x16x64_i8 v[42:45], v[66:69], v[214:217], v[42:45]
	v_mfma_i32_16x16x64_i8 v[2:5], v[126:129], v[214:217], v[2:5]
	v_mfma_i32_16x16x64_i8 v[2:5], v[178:181], v[218:221], v[2:5]
	v_mfma_i32_16x16x64_i8 v[22:25], v[178:181], v[186:189], v[22:25]
	v_mfma_i32_16x16x64_i8 v[22:25], v[126:129], v[182:185], v[22:25]
	v_mfma_i32_16x16x64_i8 v[30:33], v[114:117], v[182:185], v[30:33]
	v_mfma_i32_16x16x64_i8 v[30:33], v[118:121], v[186:189], v[30:33]
	v_mfma_i32_16x16x64_i8 v[26:29], v[118:121], v[194:197], v[26:29]
	v_mfma_i32_16x16x64_i8 v[26:29], v[114:117], v[190:193], v[26:29]
	v_mfma_i32_16x16x64_i8 v[14:17], v[126:129], v[190:193], v[14:17]
	v_mfma_i32_16x16x64_i8 v[14:17], v[178:181], v[194:197], v[14:17]
	v_mfma_i32_16x16x64_i8 v[6:9], v[178:181], v[210:213], v[6:9]
	v_mfma_i32_16x16x64_i8 v[6:9], v[126:129], v[198:201], v[6:9]
	v_mfma_i32_16x16x64_i8 v[18:21], v[114:117], v[198:201], v[18:21]
	v_mfma_i32_16x16x64_i8 v[18:21], v[118:121], v[210:213], v[18:21]
	v_mfma_i32_16x16x64_i8 v[10:13], v[118:121], v[218:221], v[10:13]
	v_mfma_i32_16x16x64_i8 v[10:13], v[114:117], v[214:217], v[10:13]
	s_barrier
	s_add_i32 s10, s10, 2
	s_add_u32 s69, s69, 0x100
	s_addc_u32 s68, s68, 0
	s_cmp_gt_u32 s10, 13
	s_mov_b64 s[8:9], s[84:85]
	s_cbranch_scc0 .LBB0_291
	s_branch .Lpeelx291
; #define PG8_STAGE(bufoff, gbase, voff) do { _Pragma("unroll") for (int _i = 0; _i < 2; ++_i) \
;         __builtin_amdgcn_global_load_lds((const unsigned*)((const char*)(gbase) + (voff)[_i]), (PG8_LAS unsigned*)(lds + (bufoff) + ldsw + _i * 8192), 16, 0, 0); } while (0)
; #define PG8_LDA(dst, b, h) do { _Pragma("unroll") for (int m = 0; m < 4; ++m) _Pragma("unroll") for (int k = 0; k < 2; ++k) dst[m][k] = *(const PG8_LAS bf16x8*)(lds + PG8_SA(b, h) + aoff + m * 2048 + k * 1024); } while (0)
; #define PG8_LDB(dst, b, h) do { _Pragma("unroll") for (int n = 0; n < 2; ++n) _Pragma("unroll") for (int k = 0; k < 2; ++k) dst[n][k] = *(const PG8_LAS bf16x8*)(lds + PG8_SB(b, h) + boff + n * 2048 + k * 1024); } while (0)
; #define PG8_MMA(ai, bj, At, Bt) do { __builtin_amdgcn_s_setprio(1); _Pragma("unroll") for (int m = 0; m < 4; ++m) _Pragma("unroll") for (int n = 0; n < 2; ++n) _Pragma("unroll") for (int k = 0; k < 2; ++k) \
;         acc[ai][bj][m][n] = mma16<Epi::I8>(Bt[n][k], At[m][k], acc[ai][bj][m][n]); __builtin_amdgcn_s_setprio(0); } while (0)
; #define PG8_WAIT_V(n) asm volatile("s_waitcnt vmcnt(" #n ")" ::: "memory")
; #define PG8_WAIT_L(n) asm volatile("s_waitcnt lgkmcnt(" #n ")" ::: "memory")
; #define PG8_BAR __builtin_amdgcn_s_barrier()
; template <class Epi, class Sched, bool ALIGN_EPI = false, bool SP2 = false>
; __device__ __forceinline__ void gemm_phase(PG8_LAS unsigned char* lds, const Gemm g, const Sched& S, const Epi& E) {
;     ...
;             const bool last = (t == nt - 2);
;             const char* a1 = cA + (size_t)(t + 1) * kstep;
;             const char* a2 = last ? nA : cA + (size_t)(t + 2) * kstep; const char* b2 = last ? nB : cB + (size_t)(t + 2) * kstep;
;             const char* a3 = a2 + kstep; const char* b3 = b2 + kstep;
;             if (last && has_next) S.a_ready(nxt);
;             if constexpr (SP2) {
;             PG8_LDB(B0, 0, 0); PG8_LDB(B1, 0, 1); PG8_SCHED; PG8_LDA(At, 0, 0); PG8_STAGE(PG8_SA(1, 1), a1 + hstep, voffA);
;             PG8_WAIT_V(8); PG8_WAIT_L(0); PG8_BAR; PG8_MMA(0, 0, At, B0); PG8_MMA(0, 1, At, B1); PG8_BAR; PG8_SCHED;
;             PG8_LDA(At, 0, 1); PG8_STAGE(PG8_SB(0, 0), b2, voffB); PG8_STAGE(PG8_SB(0, 1), b2 + hstep, voffB); PG8_STAGE(PG8_SA(0, 0), a2, voffA);
;             PG8_WAIT_V(8); PG8_WAIT_L(0); PG8_BAR; PG8_MMA(1, 0, At, B0); PG8_MMA(1, 1, At, B1); PG8_BAR; PG8_SCHED;
.LBB0_291:
	s_add_u32 s84, s8, 0x100
	s_addc_u32 s85, s9, 0
	s_add_i32 s66, 0, 0x10000
	s_cmp_eq_u32 s10, 12
	s_cselect_b32 vcc_hi, s5, s85
	s_cselect_b32 vcc_lo, s7, s84
	s_cselect_b32 s97, s11, s68
	s_cselect_b32 s96, s67, s69
	s_add_i32 s70, 0, 0x14000
	v_add_u32_e32 v110, s66, v175
	v_add_u32_e32 v168, s70, v175
	s_waitcnt vmcnt(0)
	ds_read_b128 v[66:69], v110
	ds_read_b128 v[70:73], v110 offset:1024
	ds_read_b128 v[106:109], v110 offset:2048
	ds_read_b128 v[110:113], v110 offset:3072
	ds_read_b128 v[114:117], v168
	ds_read_b128 v[118:121], v168 offset:1024
	ds_read_b128 v[126:129], v168 offset:2048
	ds_read_b128 v[178:181], v168 offset:3072
	s_add_i32 m0, s1, 0xc000
	ds_read_b128 v[182:185], v177
	ds_read_b128 v[186:189], v177 offset:1024
	ds_read_b128 v[190:193], v177 offset:2048
	ds_read_b128 v[194:197], v177 offset:3072
	ds_read_b128 v[198:201], v177 offset:4096
	ds_read_b128 v[210:213], v177 offset:5120
	ds_read_b128 v[214:217], v177 offset:6144
	ds_read_b128 v[218:221], v177 offset:7168
	global_load_lds_dwordx4 v164, s[8:9]
	s_add_i32 m0, s1, 0xe000
	s_nop 0
	global_load_lds_dwordx4 v166, s[8:9]
	s_waitcnt vmcnt(8)
	s_waitcnt lgkmcnt(0)
	s_barrier
	s_waitcnt lgkmcnt(0)
	v_mfma_i32_16x16x64_i8 v[154:157], v[66:69], v[182:185], v[154:157]
	v_mfma_i32_16x16x64_i8 v[154:157], v[70:73], v[186:189], v[154:157]
	v_mfma_i32_16x16x64_i8 v[146:149], v[110:113], v[186:189], v[146:149]
	v_mfma_i32_16x16x64_i8 v[146:149], v[106:109], v[182:185], v[146:149]
	v_mfma_i32_16x16x64_i8 v[138:141], v[106:109], v[190:193], v[138:141]
	v_mfma_i32_16x16x64_i8 v[138:141], v[110:113], v[194:197], v[138:141]
	v_mfma_i32_16x16x64_i8 v[150:153], v[70:73], v[194:197], v[150:153]
	v_mfma_i32_16x16x64_i8 v[150:153], v[66:69], v[190:193], v[150:153]
	v_mfma_i32_16x16x64_i8 v[142:145], v[66:69], v[198:201], v[142:145]
	v_mfma_i32_16x16x64_i8 v[142:145], v[70:73], v[210:213], v[142:145]
	v_mfma_i32_16x16x64_i8 v[130:133], v[110:113], v[210:213], v[130:133]
	v_mfma_i32_16x16x64_i8 v[130:133], v[106:109], v[198:201], v[130:133]
	v_mfma_i32_16x16x64_i8 v[122:125], v[106:109], v[214:217], v[122:125]
	v_mfma_i32_16x16x64_i8 v[122:125], v[110:113], v[218:221], v[122:125]
	v_mfma_i32_16x16x64_i8 v[134:137], v[70:73], v[218:221], v[134:137]
	v_mfma_i32_16x16x64_i8 v[134:137], v[66:69], v[214:217], v[134:137]
	v_mfma_i32_16x16x64_i8 v[74:77], v[126:129], v[214:217], v[74:77]
	v_mfma_i32_16x16x64_i8 v[74:77], v[178:181], v[218:221], v[74:77]
	v_mfma_i32_16x16x64_i8 v[94:97], v[178:181], v[186:189], v[94:97]
	v_mfma_i32_16x16x64_i8 v[94:97], v[126:129], v[182:185], v[94:97]
	v_mfma_i32_16x16x64_i8 v[102:105], v[114:117], v[182:185], v[102:105]
	v_mfma_i32_16x16x64_i8 v[102:105], v[118:121], v[186:189], v[102:105]
	v_mfma_i32_16x16x64_i8 v[98:101], v[118:121], v[194:197], v[98:101]
	v_mfma_i32_16x16x64_i8 v[98:101], v[114:117], v[190:193], v[98:101]
	v_mfma_i32_16x16x64_i8 v[86:89], v[126:129], v[190:193], v[86:89]
	v_mfma_i32_16x16x64_i8 v[86:89], v[178:181], v[194:197], v[86:89]
	v_mfma_i32_16x16x64_i8 v[78:81], v[178:181], v[210:213], v[78:81]
	v_mfma_i32_16x16x64_i8 v[78:81], v[126:129], v[198:201], v[78:81]
	v_mfma_i32_16x16x64_i8 v[90:93], v[114:117], v[198:201], v[90:93]
	v_mfma_i32_16x16x64_i8 v[90:93], v[118:121], v[210:213], v[90:93]
	v_mfma_i32_16x16x64_i8 v[82:85], v[118:121], v[218:221], v[82:85]
	v_mfma_i32_16x16x64_i8 v[82:85], v[114:117], v[214:217], v[82:85]
	s_barrier
	s_add_i32 s8, s66, s81
	s_mov_b32 m0, s8
	ds_read_b128 v[182:185], v177 offset:16384
	ds_read_b128 v[186:189], v177 offset:17408
	ds_read_b128 v[190:193], v177 offset:18432
	ds_read_b128 v[194:197], v177 offset:19456
	ds_read_b128 v[198:201], v177 offset:20480
	ds_read_b128 v[210:213], v177 offset:21504
	ds_read_b128 v[214:217], v177 offset:22528
	ds_read_b128 v[218:221], v177 offset:23552
	global_load_lds_dwordx4 v0, s[96:97]
	s_add_i32 m0, s8, 0x2000
	s_add_u32 s8, s96, 0x40000
	s_addc_u32 s9, s97, 0
	s_add_i32 s66, s70, s81
	global_load_lds_dwordx4 v158, s[96:97]
	s_mov_b32 m0, s66
	s_nop 0
	global_load_lds_dwordx4 v0, s[8:9]
	s_add_i32 m0, s66, 0x2000
	s_nop 0
	global_load_lds_dwordx4 v158, s[8:9]
	s_mov_b32 m0, s1
	s_nop 0
	global_load_lds_dwordx4 v162, vcc
	s_mov_b32 m0, s58
	s_nop 0
	global_load_lds_dwordx4 v160, vcc
	s_waitcnt vmcnt(8)
	s_waitcnt lgkmcnt(0)
	s_barrier
	s_waitcnt lgkmcnt(0)
	v_mfma_i32_16x16x64_i8 v[62:65], v[66:69], v[182:185], v[62:65]
	v_mfma_i32_16x16x64_i8 v[62:65], v[70:73], v[186:189], v[62:65]
	v_mfma_i32_16x16x64_i8 v[54:57], v[110:113], v[186:189], v[54:57]
	v_mfma_i32_16x16x64_i8 v[54:57], v[106:109], v[182:185], v[54:57]
	v_mfma_i32_16x16x64_i8 v[46:49], v[106:109], v[190:193], v[46:49]
	v_mfma_i32_16x16x64_i8 v[46:49], v[110:113], v[194:197], v[46:49]
	v_mfma_i32_16x16x64_i8 v[58:61], v[70:73], v[194:197], v[58:61]
	v_mfma_i32_16x16x64_i8 v[58:61], v[66:69], v[190:193], v[58:61]
	v_mfma_i32_16x16x64_i8 v[50:53], v[66:69], v[198:201], v[50:53]
	v_mfma_i32_16x16x64_i8 v[50:53], v[70:73], v[210:213], v[50:53]
	v_mfma_i32_16x16x64_i8 v[38:41], v[110:113], v[210:213], v[38:41]
	v_mfma_i32_16x16x64_i8 v[38:41], v[106:109], v[198:201], v[38:41]
	v_mfma_i32_16x16x64_i8 v[34:37], v[106:109], v[214:217], v[34:37]
	v_mfma_i32_16x16x64_i8 v[34:37], v[110:113], v[218:221], v[34:37]
	v_mfma_i32_16x16x64_i8 v[42:45], v[70:73], v[218:221], v[42:45]
	v_mfma_i32_16x16x64_i8 v[42:45], v[66:69], v[214:217], v[42:45]
	v_mfma_i32_16x16x64_i8 v[2:5], v[126:129], v[214:217], v[2:5]
	v_mfma_i32_16x16x64_i8 v[2:5], v[178:181], v[218:221], v[2:5]
	v_mfma_i32_16x16x64_i8 v[22:25], v[178:181], v[186:189], v[22:25]
	v_mfma_i32_16x16x64_i8 v[22:25], v[126:129], v[182:185], v[22:25]
	v_mfma_i32_16x16x64_i8 v[30:33], v[114:117], v[182:185], v[30:33]
	v_mfma_i32_16x16x64_i8 v[30:33], v[118:121], v[186:189], v[30:33]
	v_mfma_i32_16x16x64_i8 v[26:29], v[118:121], v[194:197], v[26:29]
	v_mfma_i32_16x16x64_i8 v[26:29], v[114:117], v[190:193], v[26:29]
	v_mfma_i32_16x16x64_i8 v[14:17], v[126:129], v[190:193], v[14:17]
	v_mfma_i32_16x16x64_i8 v[14:17], v[178:181], v[194:197], v[14:17]
	v_mfma_i32_16x16x64_i8 v[6:9], v[178:181], v[210:213], v[6:9]
	v_mfma_i32_16x16x64_i8 v[6:9], v[126:129], v[198:201], v[6:9]
	v_mfma_i32_16x16x64_i8 v[18:21], v[114:117], v[198:201], v[18:21]
	v_mfma_i32_16x16x64_i8 v[18:21], v[118:121], v[210:213], v[18:21]
	v_mfma_i32_16x16x64_i8 v[10:13], v[118:121], v[218:221], v[10:13]
	v_mfma_i32_16x16x64_i8 v[10:13], v[114:117], v[214:217], v[10:13]
	s_barrier
; #define PG8_STAGE(bufoff, gbase, voff) do { _Pragma("unroll") for (int _i = 0; _i < 2; ++_i) \
;         __builtin_amdgcn_global_load_lds((const unsigned*)((const char*)(gbase) + (voff)[_i]), (PG8_LAS unsigned*)(lds + (bufoff) + ldsw + _i * 8192), 16, 0, 0); } while (0)
; #define PG8_LDA(dst, b, h) do { _Pragma("unroll") for (int m = 0; m < 4; ++m) _Pragma("unroll") for (int k = 0; k < 2; ++k) dst[m][k] = *(const PG8_LAS bf16x8*)(lds + PG8_SA(b, h) + aoff + m * 2048 + k * 1024); } while (0)
; #define PG8_LDB(dst, b, h) do { _Pragma("unroll") for (int n = 0; n < 2; ++n) _Pragma("unroll") for (int k = 0; k < 2; ++k) dst[n][k] = *(const PG8_LAS bf16x8*)(lds + PG8_SB(b, h) + boff + n * 2048 + k * 1024); } while (0)
; #define PG8_MMA(ai, bj, At, Bt) do { __builtin_amdgcn_s_setprio(1); _Pragma("unroll") for (int m = 0; m < 4; ++m) _Pragma("unroll") for (int n = 0; n < 2; ++n) _Pragma("unroll") for (int k = 0; k < 2; ++k) \
;         acc[ai][bj][m][n] = mma16<Epi::I8>(Bt[n][k], At[m][k], acc[ai][bj][m][n]); __builtin_amdgcn_s_setprio(0); } while (0)
; #define PG8_WAIT_V(n) asm volatile("s_waitcnt vmcnt(" #n ")" ::: "memory")
; #define PG8_WAIT_L(n) asm volatile("s_waitcnt lgkmcnt(" #n ")" ::: "memory")
; #define PG8_BAR __builtin_amdgcn_s_barrier()
; #define PG8_SCHED __builtin_amdgcn_sched_barrier(0)
; template <class Epi, class Sched, bool ALIGN_EPI = false, bool SP2 = false>
; __device__ __forceinline__ void gemm_phase(PG8_LAS unsigned char* lds, const Gemm g, const Sched& S, const Epi& E) {
;     ...
;             PG8_LDB(B0, 1, 0); PG8_LDB(B1, 1, 1); PG8_SCHED; PG8_LDA(At, 1, 0); PG8_STAGE(PG8_SA(0, 1), a2 + hstep, voffA);
;             PG8_WAIT_V(8); PG8_WAIT_L(0); PG8_BAR; PG8_MMA(0, 0, At, B0); PG8_MMA(0, 1, At, B1); PG8_BAR; PG8_SCHED;
;             PG8_LDA(At, 1, 1); PG8_STAGE(PG8_SB(1, 0), b3, voffB); PG8_STAGE(PG8_SB(1, 1), b3 + hstep, voffB); PG8_STAGE(PG8_SA(1, 0), a3, voffA);
;             PG8_WAIT_V(8); PG8_WAIT_L(0); PG8_BAR; PG8_MMA(1, 0, At, B0); PG8_MMA(1, 1, At, B1); PG8_BAR; PG8_SCHED;
	s_add_i32 s66, 0, 0x18000
	s_add_i32 s70, 0, 0x1c000
	v_add_u32_e32 v110, s66, v175
	v_add_u32_e32 v170, s70, v175
	ds_read_b128 v[66:69], v110
	ds_read_b128 v[70:73], v110 offset:1024
	ds_read_b128 v[106:109], v110 offset:2048
	ds_read_b128 v[110:113], v110 offset:3072
	ds_read_b128 v[114:117], v170
	ds_read_b128 v[118:121], v170 offset:1024
	ds_read_b128 v[126:129], v170 offset:2048
	ds_read_b128 v[178:181], v170 offset:3072
	s_add_u32 s8, vcc_lo, 0x40000
	s_addc_u32 s9, vcc_hi, 0
	s_mov_b32 m0, s80
	ds_read_b128 v[182:185], v177 offset:32768
	ds_read_b128 v[186:189], v177 offset:33792
	ds_read_b128 v[190:193], v177 offset:34816
	ds_read_b128 v[194:197], v177 offset:35840
	ds_read_b128 v[198:201], v177 offset:36864
	ds_read_b128 v[210:213], v177 offset:37888
	ds_read_b128 v[214:217], v177 offset:38912
	ds_read_b128 v[218:221], v177 offset:39936
	global_load_lds_dwordx4 v162, s[8:9]
	s_mov_b32 m0, s0
	s_nop 0
	global_load_lds_dwordx4 v160, s[8:9]
	s_waitcnt vmcnt(8)
	s_waitcnt lgkmcnt(0)
	s_barrier
	s_waitcnt lgkmcnt(0)
	v_mfma_i32_16x16x64_i8 v[154:157], v[66:69], v[182:185], v[154:157]
	v_mfma_i32_16x16x64_i8 v[154:157], v[70:73], v[186:189], v[154:157]
	v_mfma_i32_16x16x64_i8 v[146:149], v[110:113], v[186:189], v[146:149]
	v_mfma_i32_16x16x64_i8 v[146:149], v[106:109], v[182:185], v[146:149]
	v_mfma_i32_16x16x64_i8 v[138:141], v[106:109], v[190:193], v[138:141]
	v_mfma_i32_16x16x64_i8 v[138:141], v[110:113], v[194:197], v[138:141]
	v_mfma_i32_16x16x64_i8 v[150:153], v[70:73], v[194:197], v[150:153]
	v_mfma_i32_16x16x64_i8 v[150:153], v[66:69], v[190:193], v[150:153]
	v_mfma_i32_16x16x64_i8 v[142:145], v[66:69], v[198:201], v[142:145]
	v_mfma_i32_16x16x64_i8 v[142:145], v[70:73], v[210:213], v[142:145]
	v_mfma_i32_16x16x64_i8 v[130:133], v[110:113], v[210:213], v[130:133]
	v_mfma_i32_16x16x64_i8 v[130:133], v[106:109], v[198:201], v[130:133]
	v_mfma_i32_16x16x64_i8 v[122:125], v[106:109], v[214:217], v[122:125]
	v_mfma_i32_16x16x64_i8 v[122:125], v[110:113], v[218:221], v[122:125]
	v_mfma_i32_16x16x64_i8 v[134:137], v[70:73], v[218:221], v[134:137]
	v_mfma_i32_16x16x64_i8 v[134:137], v[66:69], v[214:217], v[134:137]
	v_mfma_i32_16x16x64_i8 v[74:77], v[126:129], v[214:217], v[74:77]
	v_mfma_i32_16x16x64_i8 v[74:77], v[178:181], v[218:221], v[74:77]
	v_mfma_i32_16x16x64_i8 v[94:97], v[178:181], v[186:189], v[94:97]
	v_mfma_i32_16x16x64_i8 v[94:97], v[126:129], v[182:185], v[94:97]
	v_mfma_i32_16x16x64_i8 v[102:105], v[114:117], v[182:185], v[102:105]
	v_mfma_i32_16x16x64_i8 v[102:105], v[118:121], v[186:189], v[102:105]
	v_mfma_i32_16x16x64_i8 v[98:101], v[118:121], v[194:197], v[98:101]
	v_mfma_i32_16x16x64_i8 v[98:101], v[114:117], v[190:193], v[98:101]
	v_mfma_i32_16x16x64_i8 v[86:89], v[126:129], v[190:193], v[86:89]
	v_mfma_i32_16x16x64_i8 v[86:89], v[178:181], v[194:197], v[86:89]
	v_mfma_i32_16x16x64_i8 v[78:81], v[178:181], v[210:213], v[78:81]
	v_mfma_i32_16x16x64_i8 v[78:81], v[126:129], v[198:201], v[78:81]
	v_mfma_i32_16x16x64_i8 v[90:93], v[114:117], v[198:201], v[90:93]
	v_mfma_i32_16x16x64_i8 v[90:93], v[118:121], v[210:213], v[90:93]
	v_mfma_i32_16x16x64_i8 v[82:85], v[118:121], v[218:221], v[82:85]
	v_mfma_i32_16x16x64_i8 v[82:85], v[114:117], v[214:217], v[82:85]
	s_barrier
	s_add_i32 s8, s66, s81
	s_add_u32 s98, s96, 0x80
	s_addc_u32 s99, s97, 0
	s_add_u32 s100, vcc_lo, 0x80
	s_addc_u32 s101, vcc_hi, 0
	s_mov_b32 m0, s8
	ds_read_b128 v[182:185], v177 offset:49152
	ds_read_b128 v[186:189], v177 offset:50176
	ds_read_b128 v[190:193], v177 offset:51200
	ds_read_b128 v[194:197], v177 offset:52224
	ds_read_b128 v[198:201], v177 offset:53248
	ds_read_b128 v[210:213], v177 offset:54272
	ds_read_b128 v[214:217], v177 offset:55296
	ds_read_b128 v[218:221], v177 offset:56320
	global_load_lds_dwordx4 v0, s[98:99]
	s_add_i32 m0, s8, 0x2000
	s_add_u32 s8, s96, 0x40080
	s_addc_u32 s9, s97, 0
	s_add_i32 s66, s70, s81
	global_load_lds_dwordx4 v158, s[98:99]
	s_mov_b32 m0, s66
	s_nop 0
	global_load_lds_dwordx4 v0, s[8:9]
	s_add_i32 m0, s66, 0x2000
	s_nop 0
	global_load_lds_dwordx4 v158, s[8:9]
	s_mov_b32 m0, s13
	s_nop 0
	global_load_lds_dwordx4 v162, s[100:101]
	s_mov_b32 m0, s12
	s_nop 0
	global_load_lds_dwordx4 v160, s[100:101]
	s_waitcnt vmcnt(8)
	s_waitcnt lgkmcnt(0)
	s_barrier
	s_waitcnt lgkmcnt(0)
	v_mfma_i32_16x16x64_i8 v[62:65], v[66:69], v[182:185], v[62:65]
	v_mfma_i32_16x16x64_i8 v[62:65], v[70:73], v[186:189], v[62:65]
	v_mfma_i32_16x16x64_i8 v[54:57], v[110:113], v[186:189], v[54:57]
	v_mfma_i32_16x16x64_i8 v[54:57], v[106:109], v[182:185], v[54:57]
	v_mfma_i32_16x16x64_i8 v[46:49], v[106:109], v[190:193], v[46:49]
	v_mfma_i32_16x16x64_i8 v[46:49], v[110:113], v[194:197], v[46:49]
	v_mfma_i32_16x16x64_i8 v[58:61], v[70:73], v[194:197], v[58:61]
	v_mfma_i32_16x16x64_i8 v[58:61], v[66:69], v[190:193], v[58:61]
	v_mfma_i32_16x16x64_i8 v[50:53], v[66:69], v[198:201], v[50:53]
	v_mfma_i32_16x16x64_i8 v[50:53], v[70:73], v[210:213], v[50:53]
	v_mfma_i32_16x16x64_i8 v[38:41], v[110:113], v[210:213], v[38:41]
	v_mfma_i32_16x16x64_i8 v[38:41], v[106:109], v[198:201], v[38:41]
	v_mfma_i32_16x16x64_i8 v[34:37], v[106:109], v[214:217], v[34:37]
	v_mfma_i32_16x16x64_i8 v[34:37], v[110:113], v[218:221], v[34:37]
	v_mfma_i32_16x16x64_i8 v[42:45], v[70:73], v[218:221], v[42:45]
	v_mfma_i32_16x16x64_i8 v[42:45], v[66:69], v[214:217], v[42:45]
	v_mfma_i32_16x16x64_i8 v[2:5], v[126:129], v[214:217], v[2:5]
	v_mfma_i32_16x16x64_i8 v[2:5], v[178:181], v[218:221], v[2:5]
	v_mfma_i32_16x16x64_i8 v[22:25], v[178:181], v[186:189], v[22:25]
	v_mfma_i32_16x16x64_i8 v[22:25], v[126:129], v[182:185], v[22:25]
	v_mfma_i32_16x16x64_i8 v[30:33], v[114:117], v[182:185], v[30:33]
	v_mfma_i32_16x16x64_i8 v[30:33], v[118:121], v[186:189], v[30:33]
	v_mfma_i32_16x16x64_i8 v[26:29], v[118:121], v[194:197], v[26:29]
	v_mfma_i32_16x16x64_i8 v[26:29], v[114:117], v[190:193], v[26:29]
	v_mfma_i32_16x16x64_i8 v[14:17], v[126:129], v[190:193], v[14:17]
	v_mfma_i32_16x16x64_i8 v[14:17], v[178:181], v[194:197], v[14:17]
	v_mfma_i32_16x16x64_i8 v[6:9], v[178:181], v[210:213], v[6:9]
	v_mfma_i32_16x16x64_i8 v[6:9], v[126:129], v[198:201], v[6:9]
	v_mfma_i32_16x16x64_i8 v[18:21], v[114:117], v[198:201], v[18:21]
	v_mfma_i32_16x16x64_i8 v[18:21], v[118:121], v[210:213], v[18:21]
	v_mfma_i32_16x16x64_i8 v[10:13], v[118:121], v[218:221], v[10:13]
	v_mfma_i32_16x16x64_i8 v[10:13], v[114:117], v[214:217], v[10:13]
	s_barrier
	s_add_i32 s10, s10, 2
	s_add_u32 s69, s69, 0x100
	s_addc_u32 s68, s68, 0
	s_cmp_gt_u32 s10, 13
	s_mov_b64 s[8:9], s[84:85]
	s_cbranch_scc0 .LBB0_291

; #define PG8_STAGE(bufoff, gbase, voff) do { _Pragma("unroll") for (int _i = 0; _i < 2; ++_i) \
;         __builtin_amdgcn_global_load_lds((const unsigned*)((const char*)(gbase) + (voff)[_i]), (PG8_LAS unsigned*)(lds + (bufoff) + ldsw + _i * 8192), 16, 0, 0); } while (0)
; #define PG8_LDA(dst, b, h) do { _Pragma("unroll") for (int m = 0; m < 4; ++m) _Pragma("unroll") for (int k = 0; k < 2; ++k) dst[m][k] = *(const PG8_LAS bf16x8*)(lds + PG8_SA(b, h) + aoff + m * 2048 + k * 1024); } while (0)
; #define PG8_LDB(dst, b, h) do { _Pragma("unroll") for (int n = 0; n < 2; ++n) _Pragma("unroll") for (int k = 0; k < 2; ++k) dst[n][k] = *(const PG8_LAS bf16x8*)(lds + PG8_SB(b, h) + boff + n * 2048 + k * 1024); } while (0)
; #define PG8_MMA(ai, bj, At, Bt) do { __builtin_amdgcn_s_setprio(1); _Pragma("unroll") for (int m = 0; m < 4; ++m) _Pragma("unroll") for (int n = 0; n < 2; ++n) _Pragma("unroll") for (int k = 0; k < 2; ++k) \
;         acc[ai][bj][m][n] = mma16<Epi::I8>(Bt[n][k], At[m][k], acc[ai][bj][m][n]); __builtin_amdgcn_s_setprio(0); } while (0)
; #define PG8_WAIT_V(n) asm volatile("s_waitcnt vmcnt(" #n ")" ::: "memory")
; #define PG8_WAIT_L(n) asm volatile("s_waitcnt lgkmcnt(" #n ")" ::: "memory")
; #define PG8_BAR __builtin_amdgcn_s_barrier()
; template <class Epi, class Sched, bool ALIGN_EPI = false, bool SP2 = false>
; __device__ __forceinline__ void gemm_phase(PG8_LAS unsigned char* lds, const Gemm g, const Sched& S, const Epi& E) {
;     ...
;             const bool last = (t == nt - 2);
;             const char* a1 = cA + (size_t)(t + 1) * kstep;
;             const char* a2 = last ? nA : cA + (size_t)(t + 2) * kstep; const char* b2 = last ? nB : cB + (size_t)(t + 2) * kstep;
;             const char* a3 = a2 + kstep; const char* b3 = b2 + kstep;
;             if (last && has_next) S.a_ready(nxt);
;             if constexpr (SP2) {
;             PG8_LDB(B0, 0, 0); PG8_LDB(B1, 0, 1); PG8_SCHED; PG8_LDA(At, 0, 0); PG8_STAGE(PG8_SA(1, 1), a1 + hstep, voffA);
;             PG8_WAIT_V(8); PG8_WAIT_L(0); PG8_BAR; PG8_MMA(0, 0, At, B0); PG8_MMA(0, 1, At, B1); PG8_BAR; PG8_SCHED;
;             PG8_LDA(At, 0, 1); PG8_STAGE(PG8_SB(0, 0), b2, voffB); PG8_STAGE(PG8_SB(0, 1), b2 + hstep, voffB); PG8_STAGE(PG8_SA(0, 0), a2, voffA);
;             PG8_WAIT_V(8); PG8_WAIT_L(0); PG8_BAR; PG8_MMA(1, 0, At, B0); PG8_MMA(1, 1, At, B1); PG8_BAR; PG8_SCHED;
.Lpeel385:
	s_add_u32 s70, s8, 0x100
	s_addc_u32 s71, s9, 0
	s_add_i32 s84, 0, 0x10000
	s_cmp_eq_u32 s5, 12
	s_cselect_b32 vcc_hi, s1, s71
	s_cselect_b32 vcc_lo, s7, s70
	v_add_u32_e32 v0, s84, v214
	s_cselect_b32 s83, s69, s68
	s_cselect_b32 s82, s81, s85
	s_add_i32 s10, 0, 0x14000
	ds_read_b128 v[44:47], v0
	ds_read_b128 v[52:55], v0 offset:1024
	ds_read_b128 v[60:63], v0 offset:2048
	ds_read_b128 v[64:67], v0 offset:3072
	v_add_u32_e32 v0, s10, v214
	ds_read_b128 v[84:87], v0
	ds_read_b128 v[88:91], v0 offset:1024
	ds_read_b128 v[92:95], v0 offset:2048
	ds_read_b128 v[100:103], v0 offset:3072
	s_add_i32 m0, s13, 0xc000
	ds_read_b128 v[124:127], v215
	ds_read_b128 v[128:131], v215 offset:1024
	ds_read_b128 v[140:143], v215 offset:2048
	ds_read_b128 v[188:191], v215 offset:3072
	ds_read_b128 v[192:195], v215 offset:4096
	ds_read_b128 v[196:199], v215 offset:5120
	ds_read_b128 v[216:219], v215 offset:6144
	ds_read_b128 v[220:223], v215 offset:7168
	global_load_lds_dwordx4 v184, s[8:9]
	s_add_i32 m0, s13, 0xe000
	s_nop 0
	global_load_lds_dwordx4 v186, s[8:9]
	s_waitcnt vmcnt(8)
	s_waitcnt lgkmcnt(0)
	s_barrier
	s_waitcnt lgkmcnt(0)
	v_mfma_i32_16x16x64_i8 v[172:175], v[44:47], v[124:127], 0
	v_mfma_i32_16x16x64_i8 v[172:175], v[52:55], v[128:131], v[172:175]
	v_mfma_i32_16x16x64_i8 v[164:167], v[64:67], v[128:131], 0
	v_mfma_i32_16x16x64_i8 v[164:167], v[60:63], v[124:127], v[164:167]
	v_mfma_i32_16x16x64_i8 v[160:163], v[60:63], v[140:143], 0
	v_mfma_i32_16x16x64_i8 v[160:163], v[64:67], v[188:191], v[160:163]
	v_mfma_i32_16x16x64_i8 v[168:171], v[52:55], v[188:191], 0
	v_mfma_i32_16x16x64_i8 v[168:171], v[44:47], v[140:143], v[168:171]
	v_mfma_i32_16x16x64_i8 v[156:159], v[44:47], v[192:195], 0
	v_mfma_i32_16x16x64_i8 v[156:159], v[52:55], v[196:199], v[156:159]
	v_mfma_i32_16x16x64_i8 v[152:155], v[64:67], v[196:199], 0
	v_mfma_i32_16x16x64_i8 v[152:155], v[60:63], v[192:195], v[152:155]
	v_mfma_i32_16x16x64_i8 v[144:147], v[60:63], v[216:219], 0
	v_mfma_i32_16x16x64_i8 v[144:147], v[64:67], v[220:223], v[144:147]
	v_mfma_i32_16x16x64_i8 v[148:151], v[52:55], v[220:223], 0
	v_mfma_i32_16x16x64_i8 v[148:151], v[44:47], v[216:219], v[148:151]
	v_mfma_i32_16x16x64_i8 v[104:107], v[84:87], v[216:219], 0
	v_mfma_i32_16x16x64_i8 v[104:107], v[88:91], v[220:223], v[104:107]
	v_mfma_i32_16x16x64_i8 v[136:139], v[88:91], v[128:131], 0
	v_mfma_i32_16x16x64_i8 v[136:139], v[84:87], v[124:127], v[136:139]
	v_mfma_i32_16x16x64_i8 v[120:123], v[92:95], v[124:127], 0
	v_mfma_i32_16x16x64_i8 v[120:123], v[100:103], v[128:131], v[120:123]
	v_mfma_i32_16x16x64_i8 v[116:119], v[100:103], v[188:191], 0
	v_mfma_i32_16x16x64_i8 v[116:119], v[92:95], v[140:143], v[116:119]
	v_mfma_i32_16x16x64_i8 v[108:111], v[92:95], v[192:195], 0
	v_mfma_i32_16x16x64_i8 v[108:111], v[100:103], v[196:199], v[108:111]
	v_mfma_i32_16x16x64_i8 v[112:115], v[88:91], v[196:199], 0
	v_mfma_i32_16x16x64_i8 v[112:115], v[84:87], v[192:195], v[112:115]
	v_mfma_i32_16x16x64_i8 v[124:127], v[84:87], v[140:143], 0
	v_mfma_i32_16x16x64_i8 v[124:127], v[88:91], v[188:191], v[124:127]
	v_mfma_i32_16x16x64_i8 v[96:99], v[92:95], v[216:219], 0
	v_mfma_i32_16x16x64_i8 v[96:99], v[100:103], v[220:223], v[96:99]
	s_barrier
	s_add_i32 s8, s84, s12
	s_mov_b32 m0, s8
	ds_read_b128 v[128:131], v215 offset:16384
	ds_read_b128 v[132:135], v215 offset:17408
	ds_read_b128 v[140:143], v215 offset:18432
	ds_read_b128 v[188:191], v215 offset:19456
	ds_read_b128 v[192:195], v215 offset:20480
	ds_read_b128 v[196:199], v215 offset:21504
	ds_read_b128 v[216:219], v215 offset:22528
	ds_read_b128 v[220:223], v215 offset:23552
	global_load_lds_dwordx4 v178, s[82:83]
	s_add_i32 m0, s8, 0x2000
	s_add_u32 s8, s82, 0x40000
	s_addc_u32 s9, s83, 0
	s_add_i32 s10, s10, s12
	global_load_lds_dwordx4 v182, s[82:83]
	s_mov_b32 m0, s10
	s_nop 0
	global_load_lds_dwordx4 v178, s[8:9]
	s_add_i32 m0, s10, 0x2000
	s_nop 0
	global_load_lds_dwordx4 v182, s[8:9]
	s_mov_b32 m0, s13
	s_nop 0
	global_load_lds_dwordx4 v176, vcc
	s_mov_b32 m0, s66
	s_nop 0
	global_load_lds_dwordx4 v180, vcc
	s_waitcnt vmcnt(8)
	s_waitcnt lgkmcnt(0)
	s_barrier
	s_waitcnt lgkmcnt(0)
	v_mfma_i32_16x16x64_i8 v[80:83], v[44:47], v[128:131], 0
	v_mfma_i32_16x16x64_i8 v[80:83], v[52:55], v[132:135], v[80:83]
	v_mfma_i32_16x16x64_i8 v[72:75], v[64:67], v[132:135], 0
	v_mfma_i32_16x16x64_i8 v[72:75], v[60:63], v[128:131], v[72:75]
	v_mfma_i32_16x16x64_i8 v[68:71], v[60:63], v[140:143], 0
	v_mfma_i32_16x16x64_i8 v[68:71], v[64:67], v[188:191], v[68:71]
	v_mfma_i32_16x16x64_i8 v[76:79], v[52:55], v[188:191], 0
	v_mfma_i32_16x16x64_i8 v[76:79], v[44:47], v[140:143], v[76:79]
	v_mfma_i32_16x16x64_i8 v[56:59], v[44:47], v[192:195], 0
	v_mfma_i32_16x16x64_i8 v[56:59], v[52:55], v[196:199], v[56:59]
	v_mfma_i32_16x16x64_i8 v[48:51], v[64:67], v[196:199], 0
	v_mfma_i32_16x16x64_i8 v[48:51], v[60:63], v[192:195], v[48:51]
	v_mfma_i32_16x16x64_i8 v[36:39], v[60:63], v[216:219], 0
	v_mfma_i32_16x16x64_i8 v[36:39], v[64:67], v[220:223], v[36:39]
	v_mfma_i32_16x16x64_i8 v[40:43], v[52:55], v[220:223], 0
	v_mfma_i32_16x16x64_i8 v[40:43], v[44:47], v[216:219], v[40:43]
	v_mfma_i32_16x16x64_i8 v[2:5], v[92:95], v[216:219], 0
	v_mfma_i32_16x16x64_i8 v[2:5], v[100:103], v[220:223], v[2:5]
	v_mfma_i32_16x16x64_i8 v[24:27], v[100:103], v[132:135], 0
	v_mfma_i32_16x16x64_i8 v[24:27], v[92:95], v[128:131], v[24:27]
	v_mfma_i32_16x16x64_i8 v[32:35], v[84:87], v[128:131], 0
	v_mfma_i32_16x16x64_i8 v[32:35], v[88:91], v[132:135], v[32:35]
	v_mfma_i32_16x16x64_i8 v[28:31], v[88:91], v[188:191], 0
	v_mfma_i32_16x16x64_i8 v[28:31], v[84:87], v[140:143], v[28:31]
	v_mfma_i32_16x16x64_i8 v[20:23], v[92:95], v[140:143], 0
	v_mfma_i32_16x16x64_i8 v[20:23], v[100:103], v[188:191], v[20:23]
	v_mfma_i32_16x16x64_i8 v[12:15], v[100:103], v[196:199], 0
	v_mfma_i32_16x16x64_i8 v[12:15], v[92:95], v[192:195], v[12:15]
	v_mfma_i32_16x16x64_i8 v[16:19], v[84:87], v[192:195], 0
	v_mfma_i32_16x16x64_i8 v[16:19], v[88:91], v[196:199], v[16:19]
	v_mfma_i32_16x16x64_i8 v[8:11], v[88:91], v[220:223], 0
	v_mfma_i32_16x16x64_i8 v[8:11], v[84:87], v[216:219], v[8:11]
	s_barrier
; #define PG8_STAGE(bufoff, gbase, voff) do { _Pragma("unroll") for (int _i = 0; _i < 2; ++_i) \
;         __builtin_amdgcn_global_load_lds((const unsigned*)((const char*)(gbase) + (voff)[_i]), (PG8_LAS unsigned*)(lds + (bufoff) + ldsw + _i * 8192), 16, 0, 0); } while (0)
; #define PG8_LDA(dst, b, h) do { _Pragma("unroll") for (int m = 0; m < 4; ++m) _Pragma("unroll") for (int k = 0; k < 2; ++k) dst[m][k] = *(const PG8_LAS bf16x8*)(lds + PG8_SA(b, h) + aoff + m * 2048 + k * 1024); } while (0)
; #define PG8_LDB(dst, b, h) do { _Pragma("unroll") for (int n = 0; n < 2; ++n) _Pragma("unroll") for (int k = 0; k < 2; ++k) dst[n][k] = *(const PG8_LAS bf16x8*)(lds + PG8_SB(b, h) + boff + n * 2048 + k * 1024); } while (0)
; #define PG8_MMA(ai, bj, At, Bt) do { __builtin_amdgcn_s_setprio(1); _Pragma("unroll") for (int m = 0; m < 4; ++m) _Pragma("unroll") for (int n = 0; n < 2; ++n) _Pragma("unroll") for (int k = 0; k < 2; ++k) \
;         acc[ai][bj][m][n] = mma16<Epi::I8>(Bt[n][k], At[m][k], acc[ai][bj][m][n]); __builtin_amdgcn_s_setprio(0); } while (0)
; #define PG8_WAIT_V(n) asm volatile("s_waitcnt vmcnt(" #n ")" ::: "memory")
; #define PG8_WAIT_L(n) asm volatile("s_waitcnt lgkmcnt(" #n ")" ::: "memory")
; #define PG8_BAR __builtin_amdgcn_s_barrier()
; #define PG8_SCHED __builtin_amdgcn_sched_barrier(0)
; template <class Epi, class Sched, bool ALIGN_EPI = false, bool SP2 = false>
; __device__ __forceinline__ void gemm_phase(PG8_LAS unsigned char* lds, const Gemm g, const Sched& S, const Epi& E) {
;     ...
;             PG8_LDB(B0, 1, 0); PG8_LDB(B1, 1, 1); PG8_SCHED; PG8_LDA(At, 1, 0); PG8_STAGE(PG8_SA(0, 1), a2 + hstep, voffA);
;             PG8_WAIT_V(8); PG8_WAIT_L(0); PG8_BAR; PG8_MMA(0, 0, At, B0); PG8_MMA(0, 1, At, B1); PG8_BAR; PG8_SCHED;
;             PG8_LDA(At, 1, 1); PG8_STAGE(PG8_SB(1, 0), b3, voffB); PG8_STAGE(PG8_SB(1, 1), b3 + hstep, voffB); PG8_STAGE(PG8_SA(1, 0), a3, voffA);
;             PG8_WAIT_V(8); PG8_WAIT_L(0); PG8_BAR; PG8_MMA(1, 0, At, B0); PG8_MMA(1, 1, At, B1); PG8_BAR; PG8_SCHED;
	s_add_i32 s10, 0, 0x18000
	v_add_u32_e32 v0, s10, v214
	s_add_i32 s11, 0, 0x1c000
	ds_read_b128 v[44:47], v0
	ds_read_b128 v[52:55], v0 offset:1024
	ds_read_b128 v[60:63], v0 offset:2048
	ds_read_b128 v[64:67], v0 offset:3072
	v_add_u32_e32 v0, s11, v214
	ds_read_b128 v[84:87], v0
	ds_read_b128 v[88:91], v0 offset:1024
	ds_read_b128 v[92:95], v0 offset:2048
	ds_read_b128 v[100:103], v0 offset:3072
	s_add_u32 s8, vcc_lo, 0x40000
	s_addc_u32 s9, vcc_hi, 0
	s_mov_b32 m0, s67
	ds_read_b128 v[128:131], v215 offset:32768
	ds_read_b128 v[132:135], v215 offset:33792
	ds_read_b128 v[140:143], v215 offset:34816
	ds_read_b128 v[188:191], v215 offset:35840
	ds_read_b128 v[192:195], v215 offset:36864
	ds_read_b128 v[196:199], v215 offset:37888
	ds_read_b128 v[216:219], v215 offset:38912
	ds_read_b128 v[220:223], v215 offset:39936
	global_load_lds_dwordx4 v176, s[8:9]
	s_mov_b32 m0, s80
	s_nop 0
	global_load_lds_dwordx4 v180, s[8:9]
	s_waitcnt vmcnt(8)
	s_waitcnt lgkmcnt(0)
	s_barrier
	s_waitcnt lgkmcnt(0)
	v_mfma_i32_16x16x64_i8 v[172:175], v[44:47], v[128:131], v[172:175]
	v_mfma_i32_16x16x64_i8 v[172:175], v[52:55], v[132:135], v[172:175]
	v_mfma_i32_16x16x64_i8 v[164:167], v[60:63], v[128:131], v[164:167]
	v_mfma_i32_16x16x64_i8 v[164:167], v[64:67], v[132:135], v[164:167]
	v_mfma_i32_16x16x64_i8 v[160:163], v[60:63], v[140:143], v[160:163]
	v_mfma_i32_16x16x64_i8 v[160:163], v[64:67], v[188:191], v[160:163]
	v_mfma_i32_16x16x64_i8 v[168:171], v[44:47], v[140:143], v[168:171]
	v_mfma_i32_16x16x64_i8 v[168:171], v[52:55], v[188:191], v[168:171]
	v_mfma_i32_16x16x64_i8 v[156:159], v[44:47], v[192:195], v[156:159]
	v_mfma_i32_16x16x64_i8 v[156:159], v[52:55], v[196:199], v[156:159]
	v_mfma_i32_16x16x64_i8 v[152:155], v[60:63], v[192:195], v[152:155]
	v_mfma_i32_16x16x64_i8 v[152:155], v[64:67], v[196:199], v[152:155]
	v_mfma_i32_16x16x64_i8 v[144:147], v[60:63], v[216:219], v[144:147]
	v_mfma_i32_16x16x64_i8 v[144:147], v[64:67], v[220:223], v[144:147]
	v_mfma_i32_16x16x64_i8 v[148:151], v[44:47], v[216:219], v[148:151]
	v_mfma_i32_16x16x64_i8 v[148:151], v[52:55], v[220:223], v[148:151]
	v_mfma_i32_16x16x64_i8 v[136:139], v[84:87], v[128:131], v[136:139]
	v_mfma_i32_16x16x64_i8 v[136:139], v[88:91], v[132:135], v[136:139]
	v_mfma_i32_16x16x64_i8 v[120:123], v[92:95], v[128:131], v[120:123]
	v_mfma_i32_16x16x64_i8 v[120:123], v[100:103], v[132:135], v[120:123]
	v_mfma_i32_16x16x64_i8 v[116:119], v[92:95], v[140:143], v[116:119]
	v_mfma_i32_16x16x64_i8 v[116:119], v[100:103], v[188:191], v[116:119]
	v_mfma_i32_16x16x64_i8 v[124:127], v[84:87], v[140:143], v[124:127]
	v_mfma_i32_16x16x64_i8 v[132:135], v[88:91], v[188:191], v[124:127]
	v_mfma_i32_16x16x64_i8 v[112:115], v[84:87], v[192:195], v[112:115]
	v_mfma_i32_16x16x64_i8 v[112:115], v[88:91], v[196:199], v[112:115]
	v_mfma_i32_16x16x64_i8 v[108:111], v[92:95], v[192:195], v[108:111]
	v_mfma_i32_16x16x64_i8 v[108:111], v[100:103], v[196:199], v[108:111]
	v_mfma_i32_16x16x64_i8 v[96:99], v[92:95], v[216:219], v[96:99]
	v_mfma_i32_16x16x64_i8 v[96:99], v[100:103], v[220:223], v[96:99]
	v_mfma_i32_16x16x64_i8 v[104:107], v[84:87], v[216:219], v[104:107]
	v_mfma_i32_16x16x64_i8 v[104:107], v[88:91], v[220:223], v[104:107]
	s_barrier
	s_add_i32 s8, s10, s12
	s_add_u32 s98, s82, 0x80
	s_addc_u32 s99, s83, 0
	s_add_u32 s100, vcc_lo, 0x80
	s_addc_u32 s101, vcc_hi, 0
	s_mov_b32 m0, s8
	ds_read_b128 v[124:127], v215 offset:49152
	ds_read_b128 v[128:131], v215 offset:50176
	ds_read_b128 v[140:143], v215 offset:51200
	ds_read_b128 v[188:191], v215 offset:52224
	ds_read_b128 v[192:195], v215 offset:53248
	ds_read_b128 v[196:199], v215 offset:54272
	ds_read_b128 v[216:219], v215 offset:55296
	ds_read_b128 v[220:223], v215 offset:56320
	global_load_lds_dwordx4 v178, s[98:99]
	s_add_i32 m0, s8, 0x2000
	s_add_u32 s8, s82, 0x40080
	s_addc_u32 s9, s83, 0
	s_add_i32 s10, s11, s12
	global_load_lds_dwordx4 v182, s[98:99]
	s_mov_b32 m0, s10
	s_nop 0
	global_load_lds_dwordx4 v178, s[8:9]
	s_add_i32 m0, s10, 0x2000
	s_nop 0
	global_load_lds_dwordx4 v182, s[8:9]
	s_mov_b32 m0, s58
	s_nop 0
	global_load_lds_dwordx4 v176, s[100:101]
	s_mov_b32 m0, s4
	s_nop 0
	global_load_lds_dwordx4 v180, s[100:101]
	s_waitcnt vmcnt(8)
	s_waitcnt lgkmcnt(0)
	s_barrier
	s_waitcnt lgkmcnt(0)
	v_mfma_i32_16x16x64_i8 v[80:83], v[44:47], v[124:127], v[80:83]
	v_mfma_i32_16x16x64_i8 v[80:83], v[52:55], v[128:131], v[80:83]
	v_mfma_i32_16x16x64_i8 v[72:75], v[60:63], v[124:127], v[72:75]
	v_mfma_i32_16x16x64_i8 v[72:75], v[64:67], v[128:131], v[72:75]
	v_mfma_i32_16x16x64_i8 v[68:71], v[60:63], v[140:143], v[68:71]
	v_mfma_i32_16x16x64_i8 v[68:71], v[64:67], v[188:191], v[68:71]
	v_mfma_i32_16x16x64_i8 v[76:79], v[44:47], v[140:143], v[76:79]
	v_mfma_i32_16x16x64_i8 v[76:79], v[52:55], v[188:191], v[76:79]
	v_mfma_i32_16x16x64_i8 v[56:59], v[44:47], v[192:195], v[56:59]
	v_mfma_i32_16x16x64_i8 v[56:59], v[52:55], v[196:199], v[56:59]
	v_mfma_i32_16x16x64_i8 v[48:51], v[60:63], v[192:195], v[48:51]
	v_mfma_i32_16x16x64_i8 v[48:51], v[64:67], v[196:199], v[48:51]
	v_mfma_i32_16x16x64_i8 v[36:39], v[60:63], v[216:219], v[36:39]
	v_mfma_i32_16x16x64_i8 v[36:39], v[64:67], v[220:223], v[36:39]
	v_mfma_i32_16x16x64_i8 v[40:43], v[44:47], v[216:219], v[40:43]
	v_mfma_i32_16x16x64_i8 v[40:43], v[52:55], v[220:223], v[40:43]
	v_mfma_i32_16x16x64_i8 v[32:35], v[84:87], v[124:127], v[32:35]
	v_mfma_i32_16x16x64_i8 v[32:35], v[88:91], v[128:131], v[32:35]
	v_mfma_i32_16x16x64_i8 v[24:27], v[92:95], v[124:127], v[24:27]
	v_mfma_i32_16x16x64_i8 v[24:27], v[100:103], v[128:131], v[24:27]
	v_mfma_i32_16x16x64_i8 v[20:23], v[92:95], v[140:143], v[20:23]
	v_mfma_i32_16x16x64_i8 v[20:23], v[100:103], v[188:191], v[20:23]
	v_mfma_i32_16x16x64_i8 v[28:31], v[84:87], v[140:143], v[28:31]
	v_mfma_i32_16x16x64_i8 v[28:31], v[88:91], v[188:191], v[28:31]
	v_mfma_i32_16x16x64_i8 v[16:19], v[84:87], v[192:195], v[16:19]
	v_mfma_i32_16x16x64_i8 v[16:19], v[88:91], v[196:199], v[16:19]
	v_mfma_i32_16x16x64_i8 v[12:15], v[92:95], v[192:195], v[12:15]
	v_mfma_i32_16x16x64_i8 v[12:15], v[100:103], v[196:199], v[12:15]
	v_mfma_i32_16x16x64_i8 v[2:5], v[92:95], v[216:219], v[2:5]
	v_mfma_i32_16x16x64_i8 v[6:9], v[84:87], v[216:219], v[8:11]
	v_mfma_i32_16x16x64_i8 v[8:11], v[88:91], v[220:223], v[6:9]
	v_mfma_i32_16x16x64_i8 v[4:7], v[100:103], v[220:223], v[2:5]
	s_barrier
	s_add_i32 s5, s5, 2
	s_add_u32 s85, s85, 0x100
	s_addc_u32 s68, s68, 0
	s_cmp_gt_u32 s5, 13
	s_mov_b64 s[8:9], s[70:71]
	s_cbranch_scc0 .LBB0_385
	s_branch .Lpeelx385
